# GEMM K-loops: priorities inverted (load segments at priority 1, MFMA bursts at 0)
# speedup vs baseline: 1.0112x; 1.0112x over previous
.Lskw_P1:
	s_waitcnt lgkmcnt(0)
	s_barrier
	s_setprio 0
	s_waitcnt lgkmcnt(0)
	v_mfma_f32_16x16x32_bf16 v[124:127], v[148:151], v[186:189], v[124:127]
	v_mfma_f32_16x16x32_bf16 v[120:123], v[156:159], v[186:189], v[120:123]
	v_mfma_f32_16x16x32_bf16 v[108:111], v[148:151], v[194:197], v[108:111]
	v_mfma_f32_16x16x32_bf16 v[104:107], v[156:159], v[194:197], v[104:107]
	v_mfma_f32_16x16x32_bf16 v[92:95], v[148:151], v[202:205], v[92:95]
	v_mfma_f32_16x16x32_bf16 v[88:91], v[156:159], v[202:205], v[88:91]
	v_mfma_f32_16x16x32_bf16 v[76:79], v[148:151], v[210:213], v[76:79]
	v_mfma_f32_16x16x32_bf16 v[72:75], v[156:159], v[210:213], v[72:75]
	v_mfma_f32_16x16x32_bf16 v[124:127], v[152:155], v[190:193], v[124:127]
	v_mfma_f32_16x16x32_bf16 v[120:123], v[160:163], v[190:193], v[120:123]
	v_mfma_f32_16x16x32_bf16 v[108:111], v[152:155], v[198:201], v[108:111]
	v_mfma_f32_16x16x32_bf16 v[104:107], v[160:163], v[198:201], v[104:107]
	v_mfma_f32_16x16x32_bf16 v[92:95], v[152:155], v[206:209], v[92:95]
	v_mfma_f32_16x16x32_bf16 v[88:91], v[160:163], v[206:209], v[88:91]
	v_mfma_f32_16x16x32_bf16 v[76:79], v[152:155], v[214:217], v[76:79]
	v_mfma_f32_16x16x32_bf16 v[72:75], v[160:163], v[214:217], v[72:75]
	s_setprio 1
	s_setprio 0
	v_mfma_f32_16x16x32_bf16 v[116:119], v[164:167], v[186:189], v[116:119]
	v_mfma_f32_16x16x32_bf16 v[112:115], v[178:181], v[186:189], v[112:115]
	v_mfma_f32_16x16x32_bf16 v[100:103], v[164:167], v[194:197], v[100:103]
	v_mfma_f32_16x16x32_bf16 v[96:99], v[178:181], v[194:197], v[96:99]
	v_mfma_f32_16x16x32_bf16 v[84:87], v[164:167], v[202:205], v[84:87]
	v_mfma_f32_16x16x32_bf16 v[80:83], v[178:181], v[202:205], v[80:83]
	v_mfma_f32_16x16x32_bf16 v[68:71], v[164:167], v[210:213], v[68:71]
	v_mfma_f32_16x16x32_bf16 v[64:67], v[178:181], v[210:213], v[64:67]
	v_mfma_f32_16x16x32_bf16 v[116:119], v[168:171], v[190:193], v[116:119]
	v_mfma_f32_16x16x32_bf16 v[112:115], v[182:185], v[190:193], v[112:115]
	v_mfma_f32_16x16x32_bf16 v[100:103], v[168:171], v[198:201], v[100:103]
	v_mfma_f32_16x16x32_bf16 v[96:99], v[182:185], v[198:201], v[96:99]
	v_mfma_f32_16x16x32_bf16 v[84:87], v[168:171], v[206:209], v[84:87]
	v_mfma_f32_16x16x32_bf16 v[80:83], v[182:185], v[206:209], v[80:83]
	v_mfma_f32_16x16x32_bf16 v[68:71], v[168:171], v[214:217], v[68:71]
	v_mfma_f32_16x16x32_bf16 v[64:67], v[182:185], v[214:217], v[64:67]
	s_setprio 1
	s_barrier
	s_add_i32 s27, s64, s50
	v_lshl_add_u64 v[218:219], s[44:45], 0, v[130:131]
	s_mov_b32 m0, s27
	ds_read_b128 v[186:189], v177 offset:16384
	ds_read_b128 v[190:193], v177 offset:17408
	ds_read_b128 v[194:197], v177 offset:18432
	ds_read_b128 v[198:201], v177 offset:19456
	ds_read_b128 v[202:205], v177 offset:20480
	ds_read_b128 v[206:209], v177 offset:21504
	ds_read_b128 v[210:213], v177 offset:22528
	ds_read_b128 v[214:217], v177 offset:23552
	global_load_lds_dwordx4 v[218:219], off
	s_add_i32 m0, s27, 0x2000
	s_add_u32 s34, s44, 0x40000
	v_lshl_add_u64 v[220:221], s[44:45], 0, v[134:135]
	s_addc_u32 s35, s45, 0
	s_add_i32 s27, s65, s50
	global_load_lds_dwordx4 v[220:221], off
	v_lshl_add_u64 v[222:223], s[34:35], 0, v[130:131]
	s_mov_b32 m0, s27
	v_lshl_add_u64 v[224:225], s[46:47], 0, v[132:133]
	global_load_lds_dwordx4 v[222:223], off
	v_lshl_add_u64 v[222:223], s[34:35], 0, v[134:135]
	s_add_i32 m0, s27, 0x2000
	s_nop 0
	global_load_lds_dwordx4 v[222:223], off
	v_lshl_add_u64 v[222:223], s[46:47], 0, v[128:129]
	s_mov_b32 m0, s51
	s_nop 0
	global_load_lds_dwordx4 v[222:223], off
	s_mov_b32 m0, s52
	s_nop 0
	global_load_lds_dwordx4 v[224:225], off
	s_waitcnt vmcnt(8)
	s_waitcnt lgkmcnt(0)
	s_barrier
	s_setprio 0
	s_waitcnt lgkmcnt(0)
	v_mfma_f32_16x16x32_bf16 v[60:63], v[148:151], v[186:189], v[60:63]
	v_mfma_f32_16x16x32_bf16 v[56:59], v[156:159], v[186:189], v[56:59]
	v_mfma_f32_16x16x32_bf16 v[44:47], v[148:151], v[194:197], v[44:47]
	v_mfma_f32_16x16x32_bf16 v[40:43], v[156:159], v[194:197], v[40:43]
	v_mfma_f32_16x16x32_bf16 v[28:31], v[148:151], v[202:205], v[28:31]
	v_mfma_f32_16x16x32_bf16 v[24:27], v[156:159], v[202:205], v[24:27]
	v_mfma_f32_16x16x32_bf16 v[12:15], v[148:151], v[210:213], v[12:15]
	v_mfma_f32_16x16x32_bf16 v[8:11], v[156:159], v[210:213], v[8:11]
	v_mfma_f32_16x16x32_bf16 v[60:63], v[152:155], v[190:193], v[60:63]
	v_mfma_f32_16x16x32_bf16 v[56:59], v[160:163], v[190:193], v[56:59]
	v_mfma_f32_16x16x32_bf16 v[44:47], v[152:155], v[198:201], v[44:47]
	v_mfma_f32_16x16x32_bf16 v[40:43], v[160:163], v[198:201], v[40:43]
	v_mfma_f32_16x16x32_bf16 v[28:31], v[152:155], v[206:209], v[28:31]
	v_mfma_f32_16x16x32_bf16 v[24:27], v[160:163], v[206:209], v[24:27]
	v_mfma_f32_16x16x32_bf16 v[12:15], v[152:155], v[214:217], v[12:15]
	v_mfma_f32_16x16x32_bf16 v[8:11], v[160:163], v[214:217], v[8:11]
	s_setprio 1
	s_setprio 0
	v_mfma_f32_16x16x32_bf16 v[52:55], v[164:167], v[186:189], v[52:55]
	v_mfma_f32_16x16x32_bf16 v[48:51], v[178:181], v[186:189], v[48:51]
	v_mfma_f32_16x16x32_bf16 v[36:39], v[164:167], v[194:197], v[36:39]
	v_mfma_f32_16x16x32_bf16 v[32:35], v[178:181], v[194:197], v[32:35]
	v_mfma_f32_16x16x32_bf16 v[20:23], v[164:167], v[202:205], v[20:23]
	v_mfma_f32_16x16x32_bf16 v[16:19], v[178:181], v[202:205], v[16:19]
	v_mfma_f32_16x16x32_bf16 v[4:7], v[164:167], v[210:213], v[4:7]
	v_mfma_f32_16x16x32_bf16 v[0:3], v[178:181], v[210:213], v[0:3]
	v_mfma_f32_16x16x32_bf16 v[52:55], v[168:171], v[190:193], v[52:55]
	v_mfma_f32_16x16x32_bf16 v[48:51], v[182:185], v[190:193], v[48:51]
	v_mfma_f32_16x16x32_bf16 v[36:39], v[168:171], v[198:201], v[36:39]
	v_mfma_f32_16x16x32_bf16 v[32:35], v[182:185], v[198:201], v[32:35]
	v_mfma_f32_16x16x32_bf16 v[20:23], v[168:171], v[206:209], v[20:23]
	v_mfma_f32_16x16x32_bf16 v[16:19], v[182:185], v[206:209], v[16:19]
	v_mfma_f32_16x16x32_bf16 v[4:7], v[168:171], v[214:217], v[4:7]
	v_mfma_f32_16x16x32_bf16 v[0:3], v[182:185], v[214:217], v[0:3]
	s_setprio 1
	s_barrier
	s_add_i32 s27, 0, 0x18000
	v_add_u32_e32 v136, s27, v173
	s_add_i32 s30, 0, 0x1c000
	ds_read_b128 v[148:151], v136
	ds_read_b128 v[152:155], v136 offset:1024
	ds_read_b128 v[156:159], v136 offset:2048
	ds_read_b128 v[160:163], v136 offset:3072
	v_add_u32_e32 v136, s30, v173
	ds_read_b128 v[164:167], v136
	ds_read_b128 v[168:171], v136 offset:1024
	ds_read_b128 v[178:181], v136 offset:2048
	ds_read_b128 v[182:185], v136 offset:3072
	s_add_u32 s34, s46, 0x40000
	s_addc_u32 s35, s47, 0
	s_mov_b32 m0, s53
	v_lshl_add_u64 v[226:227], s[34:35], 0, v[128:129]
	ds_read_b128 v[186:189], v177 offset:32768
	ds_read_b128 v[190:193], v177 offset:33792
	ds_read_b128 v[194:197], v177 offset:34816
	ds_read_b128 v[198:201], v177 offset:35840
	ds_read_b128 v[202:205], v177 offset:36864
	ds_read_b128 v[206:209], v177 offset:37888
	ds_read_b128 v[210:213], v177 offset:38912
	ds_read_b128 v[214:217], v177 offset:39936
	global_load_lds_dwordx4 v[226:227], off
	v_lshl_add_u64 v[226:227], s[34:35], 0, v[132:133]
	s_mov_b32 m0, s54
	s_nop 0
	global_load_lds_dwordx4 v[226:227], off
	s_waitcnt vmcnt(8)
	s_waitcnt lgkmcnt(0)
	s_barrier
	s_setprio 0
	s_waitcnt lgkmcnt(0)
	v_mfma_f32_16x16x32_bf16 v[124:127], v[148:151], v[186:189], v[124:127]
	v_mfma_f32_16x16x32_bf16 v[120:123], v[156:159], v[186:189], v[120:123]
	v_mfma_f32_16x16x32_bf16 v[108:111], v[148:151], v[194:197], v[108:111]
	v_mfma_f32_16x16x32_bf16 v[104:107], v[156:159], v[194:197], v[104:107]
	v_mfma_f32_16x16x32_bf16 v[92:95], v[148:151], v[202:205], v[92:95]
	v_mfma_f32_16x16x32_bf16 v[88:91], v[156:159], v[202:205], v[88:91]
	v_mfma_f32_16x16x32_bf16 v[76:79], v[148:151], v[210:213], v[76:79]
	v_mfma_f32_16x16x32_bf16 v[72:75], v[156:159], v[210:213], v[72:75]
	v_mfma_f32_16x16x32_bf16 v[124:127], v[152:155], v[190:193], v[124:127]
	v_mfma_f32_16x16x32_bf16 v[120:123], v[160:163], v[190:193], v[120:123]
	v_mfma_f32_16x16x32_bf16 v[108:111], v[152:155], v[198:201], v[108:111]
	v_mfma_f32_16x16x32_bf16 v[104:107], v[160:163], v[198:201], v[104:107]
	v_mfma_f32_16x16x32_bf16 v[92:95], v[152:155], v[206:209], v[92:95]
	v_mfma_f32_16x16x32_bf16 v[88:91], v[160:163], v[206:209], v[88:91]
	v_mfma_f32_16x16x32_bf16 v[76:79], v[152:155], v[214:217], v[76:79]
	v_mfma_f32_16x16x32_bf16 v[72:75], v[160:163], v[214:217], v[72:75]
	s_setprio 1
	s_setprio 0
	v_mfma_f32_16x16x32_bf16 v[116:119], v[164:167], v[186:189], v[116:119]
	v_mfma_f32_16x16x32_bf16 v[112:115], v[178:181], v[186:189], v[112:115]
	v_mfma_f32_16x16x32_bf16 v[100:103], v[164:167], v[194:197], v[100:103]
	v_mfma_f32_16x16x32_bf16 v[96:99], v[178:181], v[194:197], v[96:99]
	v_mfma_f32_16x16x32_bf16 v[84:87], v[164:167], v[202:205], v[84:87]
	v_mfma_f32_16x16x32_bf16 v[80:83], v[178:181], v[202:205], v[80:83]
	v_mfma_f32_16x16x32_bf16 v[68:71], v[164:167], v[210:213], v[68:71]
	v_mfma_f32_16x16x32_bf16 v[64:67], v[178:181], v[210:213], v[64:67]
	v_mfma_f32_16x16x32_bf16 v[116:119], v[168:171], v[190:193], v[116:119]
	v_mfma_f32_16x16x32_bf16 v[112:115], v[182:185], v[190:193], v[112:115]
	v_mfma_f32_16x16x32_bf16 v[100:103], v[168:171], v[198:201], v[100:103]
	v_mfma_f32_16x16x32_bf16 v[96:99], v[182:185], v[198:201], v[96:99]
	v_mfma_f32_16x16x32_bf16 v[84:87], v[168:171], v[206:209], v[84:87]
	v_mfma_f32_16x16x32_bf16 v[80:83], v[182:185], v[206:209], v[80:83]
	v_mfma_f32_16x16x32_bf16 v[68:71], v[168:171], v[214:217], v[68:71]
	v_mfma_f32_16x16x32_bf16 v[64:67], v[182:185], v[214:217], v[64:67]
	s_setprio 1
	s_barrier
	s_add_i32 s27, s27, s50
	v_lshl_add_u64 v[218:219], v[218:219], 0, s[20:21]
	s_mov_b32 m0, s27
	ds_read_b128 v[186:189], v177 offset:49152
	ds_read_b128 v[190:193], v177 offset:50176
	ds_read_b128 v[194:197], v177 offset:51200
	ds_read_b128 v[198:201], v177 offset:52224
	ds_read_b128 v[202:205], v177 offset:53248
	ds_read_b128 v[206:209], v177 offset:54272
	ds_read_b128 v[210:213], v177 offset:55296
	ds_read_b128 v[214:217], v177 offset:56320
	global_load_lds_dwordx4 v[218:219], off
	s_add_i32 m0, s27, 0x2000
	s_add_u32 s34, s44, 0x40080
	v_lshl_add_u64 v[218:219], v[220:221], 0, s[20:21]
	s_addc_u32 s35, s45, 0
	s_add_i32 s27, s30, s50
	global_load_lds_dwordx4 v[218:219], off
	v_lshl_add_u64 v[218:219], s[34:35], 0, v[130:131]
	s_mov_b32 m0, s27
	s_nop 0
	global_load_lds_dwordx4 v[218:219], off
	v_lshl_add_u64 v[218:219], s[34:35], 0, v[134:135]
	s_add_i32 m0, s27, 0x2000
	s_nop 0
	global_load_lds_dwordx4 v[218:219], off
	v_lshl_add_u64 v[218:219], v[222:223], 0, s[20:21]
	s_mov_b32 m0, s62
	s_nop 0
	global_load_lds_dwordx4 v[218:219], off
	v_lshl_add_u64 v[218:219], v[224:225], 0, s[20:21]
	s_mov_b32 m0, s63
	s_nop 0
	global_load_lds_dwordx4 v[218:219], off
	s_waitcnt vmcnt(8)
	s_waitcnt lgkmcnt(0)
	s_barrier
	s_setprio 0
	s_waitcnt lgkmcnt(0)
	v_mfma_f32_16x16x32_bf16 v[60:63], v[148:151], v[186:189], v[60:63]
	v_mfma_f32_16x16x32_bf16 v[56:59], v[156:159], v[186:189], v[56:59]
	v_mfma_f32_16x16x32_bf16 v[44:47], v[148:151], v[194:197], v[44:47]
	v_mfma_f32_16x16x32_bf16 v[40:43], v[156:159], v[194:197], v[40:43]
	v_mfma_f32_16x16x32_bf16 v[28:31], v[148:151], v[202:205], v[28:31]
	v_mfma_f32_16x16x32_bf16 v[24:27], v[156:159], v[202:205], v[24:27]
	v_mfma_f32_16x16x32_bf16 v[12:15], v[148:151], v[210:213], v[12:15]
	v_mfma_f32_16x16x32_bf16 v[8:11], v[156:159], v[210:213], v[8:11]
	v_mfma_f32_16x16x32_bf16 v[60:63], v[152:155], v[190:193], v[60:63]
	v_mfma_f32_16x16x32_bf16 v[56:59], v[160:163], v[190:193], v[56:59]
	v_mfma_f32_16x16x32_bf16 v[44:47], v[152:155], v[198:201], v[44:47]
	v_mfma_f32_16x16x32_bf16 v[40:43], v[160:163], v[198:201], v[40:43]
	v_mfma_f32_16x16x32_bf16 v[28:31], v[152:155], v[206:209], v[28:31]
	v_mfma_f32_16x16x32_bf16 v[24:27], v[160:163], v[206:209], v[24:27]
	v_mfma_f32_16x16x32_bf16 v[12:15], v[152:155], v[214:217], v[12:15]
	v_mfma_f32_16x16x32_bf16 v[8:11], v[160:163], v[214:217], v[8:11]
	s_setprio 1
	s_setprio 0
	v_mfma_f32_16x16x32_bf16 v[52:55], v[164:167], v[186:189], v[52:55]
	v_mfma_f32_16x16x32_bf16 v[48:51], v[178:181], v[186:189], v[48:51]
	v_mfma_f32_16x16x32_bf16 v[36:39], v[164:167], v[194:197], v[36:39]
	v_mfma_f32_16x16x32_bf16 v[32:35], v[178:181], v[194:197], v[32:35]
	v_mfma_f32_16x16x32_bf16 v[20:23], v[164:167], v[202:205], v[20:23]
	v_mfma_f32_16x16x32_bf16 v[16:19], v[178:181], v[202:205], v[16:19]
	v_mfma_f32_16x16x32_bf16 v[4:7], v[164:167], v[210:213], v[4:7]
	v_mfma_f32_16x16x32_bf16 v[0:3], v[178:181], v[210:213], v[0:3]
	v_mfma_f32_16x16x32_bf16 v[52:55], v[168:171], v[190:193], v[52:55]
	v_mfma_f32_16x16x32_bf16 v[48:51], v[182:185], v[190:193], v[48:51]
	v_mfma_f32_16x16x32_bf16 v[36:39], v[168:171], v[198:201], v[36:39]
	v_mfma_f32_16x16x32_bf16 v[32:35], v[182:185], v[198:201], v[32:35]
	v_mfma_f32_16x16x32_bf16 v[20:23], v[168:171], v[206:209], v[20:23]
	v_mfma_f32_16x16x32_bf16 v[16:19], v[182:185], v[206:209], v[16:19]
	v_mfma_f32_16x16x32_bf16 v[4:7], v[168:171], v[214:217], v[4:7]
	v_mfma_f32_16x16x32_bf16 v[0:3], v[182:185], v[214:217], v[0:3]
	s_setprio 1
	s_barrier
	s_add_i32 s25, s25, 2
	s_add_u32 s42, s42, 0x100
	s_addc_u32 s43, s43, 0
	s_add_u32 s23, s23, 0x100
	s_addc_u32 s24, s24, 0
	s_cmp_gt_u32 s25, 13
	s_cbranch_scc0 .LBB5_248
	s_setprio 0
	s_nop 0
	s_nop 0
	s_nop 0
	s_nop 0
	s_nop 0
	s_nop 0
	s_nop 0
	s_nop 0
	s_nop 0
	s_nop 0
	s_nop 0
	s_nop 0
	s_nop 0
	s_and_b64 vcc, exec, s[18:19]
	s_cbranch_vccz .LBB5_251
	s_barrier

.Lskw_P3:
	s_waitcnt lgkmcnt(0)
	s_barrier
	s_setprio 0
	s_waitcnt lgkmcnt(0)
	v_mfma_f32_16x16x32_bf16 v[156:159], v[64:67], v[160:163], v[156:159]
	v_mfma_f32_16x16x32_bf16 v[152:155], v[72:75], v[160:163], v[152:155]
	v_mfma_f32_16x16x32_bf16 v[124:127], v[64:67], v[168:171], v[124:127]
	v_mfma_f32_16x16x32_bf16 v[120:123], v[72:75], v[168:171], v[120:123]
	v_mfma_f32_16x16x32_bf16 v[108:111], v[64:67], v[176:179], v[108:111]
	v_mfma_f32_16x16x32_bf16 v[104:107], v[72:75], v[176:179], v[104:107]
	v_mfma_f32_16x16x32_bf16 v[92:95], v[64:67], v[184:187], v[92:95]
	v_mfma_f32_16x16x32_bf16 v[88:91], v[72:75], v[184:187], v[88:91]
	v_mfma_f32_16x16x32_bf16 v[156:159], v[68:71], v[164:167], v[156:159]
	v_mfma_f32_16x16x32_bf16 v[152:155], v[76:79], v[164:167], v[152:155]
	v_mfma_f32_16x16x32_bf16 v[124:127], v[68:71], v[172:175], v[124:127]
	v_mfma_f32_16x16x32_bf16 v[120:123], v[76:79], v[172:175], v[120:123]
	v_mfma_f32_16x16x32_bf16 v[108:111], v[68:71], v[180:183], v[108:111]
	v_mfma_f32_16x16x32_bf16 v[104:107], v[76:79], v[180:183], v[104:107]
	v_mfma_f32_16x16x32_bf16 v[92:95], v[68:71], v[188:191], v[92:95]
	v_mfma_f32_16x16x32_bf16 v[88:91], v[76:79], v[188:191], v[88:91]
	s_setprio 1
	s_setprio 0
	v_mfma_f32_16x16x32_bf16 v[132:135], v[136:139], v[160:163], v[132:135]
	v_mfma_f32_16x16x32_bf16 v[128:131], v[144:147], v[160:163], v[128:131]
	v_mfma_f32_16x16x32_bf16 v[116:119], v[136:139], v[168:171], v[116:119]
	v_mfma_f32_16x16x32_bf16 v[112:115], v[144:147], v[168:171], v[112:115]
	v_mfma_f32_16x16x32_bf16 v[100:103], v[136:139], v[176:179], v[100:103]
	v_mfma_f32_16x16x32_bf16 v[96:99], v[144:147], v[176:179], v[96:99]
	v_mfma_f32_16x16x32_bf16 v[84:87], v[136:139], v[184:187], v[84:87]
	v_mfma_f32_16x16x32_bf16 v[80:83], v[144:147], v[184:187], v[80:83]
	v_mfma_f32_16x16x32_bf16 v[132:135], v[140:143], v[164:167], v[132:135]
	v_mfma_f32_16x16x32_bf16 v[128:131], v[148:151], v[164:167], v[128:131]
	v_mfma_f32_16x16x32_bf16 v[116:119], v[140:143], v[172:175], v[116:119]
	v_mfma_f32_16x16x32_bf16 v[112:115], v[148:151], v[172:175], v[112:115]
	v_mfma_f32_16x16x32_bf16 v[100:103], v[140:143], v[180:183], v[100:103]
	v_mfma_f32_16x16x32_bf16 v[96:99], v[148:151], v[180:183], v[96:99]
	v_mfma_f32_16x16x32_bf16 v[84:87], v[140:143], v[188:191], v[84:87]
	v_mfma_f32_16x16x32_bf16 v[80:83], v[148:151], v[188:191], v[80:83]
	s_setprio 1
	s_barrier
	s_add_i32 s35, s55, s46
	v_lshl_add_u64 v[192:193], s[42:43], 0, v[202:203]
	s_mov_b32 m0, s35
	ds_read_b128 v[160:163], v231 offset:16384
	ds_read_b128 v[164:167], v231 offset:17408
	ds_read_b128 v[168:171], v231 offset:18432
	ds_read_b128 v[172:175], v231 offset:19456
	ds_read_b128 v[176:179], v231 offset:20480
	ds_read_b128 v[180:183], v231 offset:21504
	ds_read_b128 v[184:187], v231 offset:22528
	ds_read_b128 v[188:191], v231 offset:23552
	global_load_lds_dwordx4 v[192:193], off
	s_add_i32 m0, s35, 0x2000
	s_add_u32 s58, s42, 0x40000
	v_lshl_add_u64 v[194:195], s[42:43], 0, v[206:207]
	s_addc_u32 s59, s43, 0
	s_add_i32 s35, s56, s46
	global_load_lds_dwordx4 v[194:195], off
	v_lshl_add_u64 v[196:197], s[58:59], 0, v[202:203]
	s_mov_b32 m0, s35
	v_lshl_add_u64 v[198:199], s[44:45], 0, v[204:205]
	global_load_lds_dwordx4 v[196:197], off
	v_lshl_add_u64 v[196:197], s[58:59], 0, v[206:207]
	s_add_i32 m0, s35, 0x2000
	s_nop 0
	global_load_lds_dwordx4 v[196:197], off
	v_lshl_add_u64 v[196:197], s[44:45], 0, v[200:201]
	s_mov_b32 m0, s39
	s_nop 0
	global_load_lds_dwordx4 v[196:197], off
	s_mov_b32 m0, s48
	s_nop 0
	global_load_lds_dwordx4 v[198:199], off
	s_waitcnt vmcnt(8)
	s_waitcnt lgkmcnt(0)
	s_barrier
	s_setprio 0
	s_waitcnt lgkmcnt(0)
	v_mfma_f32_16x16x32_bf16 v[60:63], v[64:67], v[160:163], v[60:63]
	v_mfma_f32_16x16x32_bf16 v[56:59], v[72:75], v[160:163], v[56:59]
	v_mfma_f32_16x16x32_bf16 v[44:47], v[64:67], v[168:171], v[44:47]
	v_mfma_f32_16x16x32_bf16 v[40:43], v[72:75], v[168:171], v[40:43]
	v_mfma_f32_16x16x32_bf16 v[28:31], v[64:67], v[176:179], v[28:31]
	v_mfma_f32_16x16x32_bf16 v[24:27], v[72:75], v[176:179], v[24:27]
	v_mfma_f32_16x16x32_bf16 v[12:15], v[64:67], v[184:187], v[12:15]
	v_mfma_f32_16x16x32_bf16 v[8:11], v[72:75], v[184:187], v[8:11]
	v_mfma_f32_16x16x32_bf16 v[60:63], v[68:71], v[164:167], v[60:63]
	v_mfma_f32_16x16x32_bf16 v[56:59], v[76:79], v[164:167], v[56:59]
	v_mfma_f32_16x16x32_bf16 v[44:47], v[68:71], v[172:175], v[44:47]
	v_mfma_f32_16x16x32_bf16 v[40:43], v[76:79], v[172:175], v[40:43]
	v_mfma_f32_16x16x32_bf16 v[28:31], v[68:71], v[180:183], v[28:31]
	v_mfma_f32_16x16x32_bf16 v[24:27], v[76:79], v[180:183], v[24:27]
	v_mfma_f32_16x16x32_bf16 v[12:15], v[68:71], v[188:191], v[12:15]
	v_mfma_f32_16x16x32_bf16 v[8:11], v[76:79], v[188:191], v[8:11]
	s_setprio 1
	s_setprio 0
	v_mfma_f32_16x16x32_bf16 v[52:55], v[136:139], v[160:163], v[52:55]
	v_mfma_f32_16x16x32_bf16 v[48:51], v[144:147], v[160:163], v[48:51]
	v_mfma_f32_16x16x32_bf16 v[36:39], v[136:139], v[168:171], v[36:39]
	v_mfma_f32_16x16x32_bf16 v[32:35], v[144:147], v[168:171], v[32:35]
	v_mfma_f32_16x16x32_bf16 v[20:23], v[136:139], v[176:179], v[20:23]
	v_mfma_f32_16x16x32_bf16 v[16:19], v[144:147], v[176:179], v[16:19]
	v_mfma_f32_16x16x32_bf16 v[4:7], v[136:139], v[184:187], v[4:7]
	v_mfma_f32_16x16x32_bf16 v[0:3], v[144:147], v[184:187], v[0:3]
	v_mfma_f32_16x16x32_bf16 v[52:55], v[140:143], v[164:167], v[52:55]
	v_mfma_f32_16x16x32_bf16 v[48:51], v[148:151], v[164:167], v[48:51]
	v_mfma_f32_16x16x32_bf16 v[36:39], v[140:143], v[172:175], v[36:39]
	v_mfma_f32_16x16x32_bf16 v[32:35], v[148:151], v[172:175], v[32:35]
	v_mfma_f32_16x16x32_bf16 v[20:23], v[140:143], v[180:183], v[20:23]
	v_mfma_f32_16x16x32_bf16 v[16:19], v[148:151], v[180:183], v[16:19]
	v_mfma_f32_16x16x32_bf16 v[4:7], v[140:143], v[188:191], v[4:7]
	v_mfma_f32_16x16x32_bf16 v[0:3], v[148:151], v[188:191], v[0:3]
	s_setprio 1
	s_barrier
	s_add_i32 s35, 0, 0x18000
	s_add_i32 s57, 0, 0x1c000
	v_add_u32_e32 v76, s35, v227
	v_add_u32_e32 v148, s57, v227
	ds_read_b128 v[64:67], v76
	ds_read_b128 v[68:71], v76 offset:1024
	ds_read_b128 v[72:75], v76 offset:2048
	ds_read_b128 v[76:79], v76 offset:3072
	ds_read_b128 v[136:139], v148
	ds_read_b128 v[140:143], v148 offset:1024
	ds_read_b128 v[144:147], v148 offset:2048
	ds_read_b128 v[148:151], v148 offset:3072
	s_add_u32 s44, s44, 0x40000
	s_addc_u32 s45, s45, 0
	s_mov_b32 m0, s49
	v_lshl_add_u64 v[216:217], s[44:45], 0, v[200:201]
	ds_read_b128 v[160:163], v231 offset:32768
	ds_read_b128 v[164:167], v231 offset:33792
	ds_read_b128 v[168:171], v231 offset:34816
	ds_read_b128 v[172:175], v231 offset:35840
	ds_read_b128 v[176:179], v231 offset:36864
	ds_read_b128 v[180:183], v231 offset:37888
	ds_read_b128 v[184:187], v231 offset:38912
	ds_read_b128 v[188:191], v231 offset:39936
	global_load_lds_dwordx4 v[216:217], off
	v_lshl_add_u64 v[216:217], s[44:45], 0, v[204:205]
	s_mov_b32 m0, s50
	s_nop 0
	global_load_lds_dwordx4 v[216:217], off
	s_waitcnt vmcnt(8)
	s_waitcnt lgkmcnt(0)
	s_barrier
	s_setprio 0
	s_waitcnt lgkmcnt(0)
	v_mfma_f32_16x16x32_bf16 v[156:159], v[64:67], v[160:163], v[156:159]
	v_mfma_f32_16x16x32_bf16 v[152:155], v[72:75], v[160:163], v[152:155]
	v_mfma_f32_16x16x32_bf16 v[124:127], v[64:67], v[168:171], v[124:127]
	v_mfma_f32_16x16x32_bf16 v[120:123], v[72:75], v[168:171], v[120:123]
	v_mfma_f32_16x16x32_bf16 v[108:111], v[64:67], v[176:179], v[108:111]
	v_mfma_f32_16x16x32_bf16 v[104:107], v[72:75], v[176:179], v[104:107]
	v_mfma_f32_16x16x32_bf16 v[92:95], v[64:67], v[184:187], v[92:95]
	v_mfma_f32_16x16x32_bf16 v[88:91], v[72:75], v[184:187], v[88:91]
	v_mfma_f32_16x16x32_bf16 v[156:159], v[68:71], v[164:167], v[156:159]
	v_mfma_f32_16x16x32_bf16 v[152:155], v[76:79], v[164:167], v[152:155]
	v_mfma_f32_16x16x32_bf16 v[124:127], v[68:71], v[172:175], v[124:127]
	v_mfma_f32_16x16x32_bf16 v[120:123], v[76:79], v[172:175], v[120:123]
	v_mfma_f32_16x16x32_bf16 v[108:111], v[68:71], v[180:183], v[108:111]
	v_mfma_f32_16x16x32_bf16 v[104:107], v[76:79], v[180:183], v[104:107]
	v_mfma_f32_16x16x32_bf16 v[92:95], v[68:71], v[188:191], v[92:95]
	v_mfma_f32_16x16x32_bf16 v[88:91], v[76:79], v[188:191], v[88:91]
	s_setprio 1
	s_setprio 0
	v_mfma_f32_16x16x32_bf16 v[132:135], v[136:139], v[160:163], v[132:135]
	v_mfma_f32_16x16x32_bf16 v[128:131], v[144:147], v[160:163], v[128:131]
	v_mfma_f32_16x16x32_bf16 v[116:119], v[136:139], v[168:171], v[116:119]
	v_mfma_f32_16x16x32_bf16 v[112:115], v[144:147], v[168:171], v[112:115]
	v_mfma_f32_16x16x32_bf16 v[100:103], v[136:139], v[176:179], v[100:103]
	v_mfma_f32_16x16x32_bf16 v[96:99], v[144:147], v[176:179], v[96:99]
	v_mfma_f32_16x16x32_bf16 v[84:87], v[136:139], v[184:187], v[84:87]
	v_mfma_f32_16x16x32_bf16 v[80:83], v[144:147], v[184:187], v[80:83]
	v_mfma_f32_16x16x32_bf16 v[132:135], v[140:143], v[164:167], v[132:135]
	v_mfma_f32_16x16x32_bf16 v[128:131], v[148:151], v[164:167], v[128:131]
	v_mfma_f32_16x16x32_bf16 v[116:119], v[140:143], v[172:175], v[116:119]
	v_mfma_f32_16x16x32_bf16 v[112:115], v[148:151], v[172:175], v[112:115]
	v_mfma_f32_16x16x32_bf16 v[100:103], v[140:143], v[180:183], v[100:103]
	v_mfma_f32_16x16x32_bf16 v[96:99], v[148:151], v[180:183], v[96:99]
	v_mfma_f32_16x16x32_bf16 v[84:87], v[140:143], v[188:191], v[84:87]
	v_mfma_f32_16x16x32_bf16 v[80:83], v[148:151], v[188:191], v[80:83]
	s_setprio 1
	s_barrier
	s_add_i32 s35, s35, s46
	v_lshl_add_u64 v[192:193], v[192:193], 0, s[16:17]
	s_mov_b32 m0, s35
	ds_read_b128 v[160:163], v231 offset:49152
	ds_read_b128 v[164:167], v231 offset:50176
	ds_read_b128 v[168:171], v231 offset:51200
	ds_read_b128 v[172:175], v231 offset:52224
	ds_read_b128 v[176:179], v231 offset:53248
	ds_read_b128 v[180:183], v231 offset:54272
	ds_read_b128 v[184:187], v231 offset:55296
	ds_read_b128 v[188:191], v231 offset:56320
	global_load_lds_dwordx4 v[192:193], off
	s_add_i32 m0, s35, 0x2000
	s_add_u32 s42, s42, 0x40080
	v_lshl_add_u64 v[192:193], v[194:195], 0, s[16:17]
	s_addc_u32 s43, s43, 0
	s_add_i32 s35, s57, s46
	global_load_lds_dwordx4 v[192:193], off
	v_lshl_add_u64 v[192:193], s[42:43], 0, v[202:203]
	s_mov_b32 m0, s35
	s_nop 0
	global_load_lds_dwordx4 v[192:193], off
	v_lshl_add_u64 v[192:193], s[42:43], 0, v[206:207]
	s_add_i32 m0, s35, 0x2000
	s_nop 0
	global_load_lds_dwordx4 v[192:193], off
	v_lshl_add_u64 v[192:193], v[196:197], 0, s[16:17]
	s_mov_b32 m0, s53
	s_nop 0
	global_load_lds_dwordx4 v[192:193], off
	v_lshl_add_u64 v[192:193], v[198:199], 0, s[16:17]
	s_mov_b32 m0, s54
	s_nop 0
	global_load_lds_dwordx4 v[192:193], off
	s_waitcnt vmcnt(8)
	s_waitcnt lgkmcnt(0)
	s_barrier
	s_setprio 0
	s_waitcnt lgkmcnt(0)
	v_mfma_f32_16x16x32_bf16 v[60:63], v[64:67], v[160:163], v[60:63]
	v_mfma_f32_16x16x32_bf16 v[56:59], v[72:75], v[160:163], v[56:59]
	v_mfma_f32_16x16x32_bf16 v[44:47], v[64:67], v[168:171], v[44:47]
	v_mfma_f32_16x16x32_bf16 v[40:43], v[72:75], v[168:171], v[40:43]
	v_mfma_f32_16x16x32_bf16 v[28:31], v[64:67], v[176:179], v[28:31]
	v_mfma_f32_16x16x32_bf16 v[24:27], v[72:75], v[176:179], v[24:27]
	v_mfma_f32_16x16x32_bf16 v[12:15], v[64:67], v[184:187], v[12:15]
	v_mfma_f32_16x16x32_bf16 v[8:11], v[72:75], v[184:187], v[8:11]
	v_mfma_f32_16x16x32_bf16 v[60:63], v[68:71], v[164:167], v[60:63]
	v_mfma_f32_16x16x32_bf16 v[56:59], v[76:79], v[164:167], v[56:59]
	v_mfma_f32_16x16x32_bf16 v[44:47], v[68:71], v[172:175], v[44:47]
	v_mfma_f32_16x16x32_bf16 v[40:43], v[76:79], v[172:175], v[40:43]
	v_mfma_f32_16x16x32_bf16 v[28:31], v[68:71], v[180:183], v[28:31]
	v_mfma_f32_16x16x32_bf16 v[24:27], v[76:79], v[180:183], v[24:27]
	v_mfma_f32_16x16x32_bf16 v[12:15], v[68:71], v[188:191], v[12:15]
	v_mfma_f32_16x16x32_bf16 v[8:11], v[76:79], v[188:191], v[8:11]
	s_setprio 1
	s_setprio 0
	v_mfma_f32_16x16x32_bf16 v[52:55], v[136:139], v[160:163], v[52:55]
	v_mfma_f32_16x16x32_bf16 v[48:51], v[144:147], v[160:163], v[48:51]
	v_mfma_f32_16x16x32_bf16 v[36:39], v[136:139], v[168:171], v[36:39]
	v_mfma_f32_16x16x32_bf16 v[32:35], v[144:147], v[168:171], v[32:35]
	v_mfma_f32_16x16x32_bf16 v[20:23], v[136:139], v[176:179], v[20:23]
	v_mfma_f32_16x16x32_bf16 v[16:19], v[144:147], v[176:179], v[16:19]
	v_mfma_f32_16x16x32_bf16 v[4:7], v[136:139], v[184:187], v[4:7]
	v_mfma_f32_16x16x32_bf16 v[0:3], v[144:147], v[184:187], v[0:3]
	v_mfma_f32_16x16x32_bf16 v[52:55], v[140:143], v[164:167], v[52:55]
	v_mfma_f32_16x16x32_bf16 v[48:51], v[148:151], v[164:167], v[48:51]
	v_mfma_f32_16x16x32_bf16 v[36:39], v[140:143], v[172:175], v[36:39]
	v_mfma_f32_16x16x32_bf16 v[32:35], v[148:151], v[172:175], v[32:35]
	v_mfma_f32_16x16x32_bf16 v[20:23], v[140:143], v[180:183], v[20:23]
	v_mfma_f32_16x16x32_bf16 v[16:19], v[148:151], v[180:183], v[16:19]
	v_mfma_f32_16x16x32_bf16 v[4:7], v[140:143], v[188:191], v[4:7]
	v_mfma_f32_16x16x32_bf16 v[0:3], v[148:151], v[188:191], v[0:3]
	s_setprio 1
	s_barrier
	s_add_i32 s34, s34, 2
	s_add_u32 s40, s40, 0x100
	s_addc_u32 s41, s41, 0
	s_add_u32 s30, s30, 0x100
	s_addc_u32 s33, s33, 0
	s_cmp_gt_u32 s34, 13
	s_cbranch_scc0 .LBB5_463
	s_setprio 0
	s_nop 0
	s_nop 0
	s_nop 0
	s_nop 0
	s_nop 0
	s_nop 0
	s_nop 0
	s_nop 0
	s_nop 0
	s_nop 0
	s_nop 0
	s_nop 0
	s_nop 0
	s_and_b64 vcc, exec, s[14:15]
	s_cbranch_vccz .LBB5_466
	s_barrier

.Lskw_P4:
	s_waitcnt lgkmcnt(0)
	s_barrier
	s_setprio 0
	s_waitcnt lgkmcnt(0)
	v_mfma_f32_16x16x32_bf16 v[124:127], v[128:131], v[160:163], v[124:127]
	v_mfma_f32_16x16x32_bf16 v[120:123], v[136:139], v[160:163], v[120:123]
	v_mfma_f32_16x16x32_bf16 v[108:111], v[128:131], v[168:171], v[108:111]
	v_mfma_f32_16x16x32_bf16 v[104:107], v[136:139], v[168:171], v[104:107]
	v_mfma_f32_16x16x32_bf16 v[92:95], v[128:131], v[192:195], v[92:95]
	v_mfma_f32_16x16x32_bf16 v[88:91], v[136:139], v[192:195], v[88:91]
	v_mfma_f32_16x16x32_bf16 v[76:79], v[128:131], v[200:203], v[76:79]
	v_mfma_f32_16x16x32_bf16 v[72:75], v[136:139], v[200:203], v[72:75]
	v_mfma_f32_16x16x32_bf16 v[124:127], v[132:135], v[164:167], v[124:127]
	v_mfma_f32_16x16x32_bf16 v[120:123], v[140:143], v[164:167], v[120:123]
	v_mfma_f32_16x16x32_bf16 v[108:111], v[132:135], v[172:175], v[108:111]
	v_mfma_f32_16x16x32_bf16 v[104:107], v[140:143], v[172:175], v[104:107]
	v_mfma_f32_16x16x32_bf16 v[92:95], v[132:135], v[196:199], v[92:95]
	v_mfma_f32_16x16x32_bf16 v[88:91], v[140:143], v[196:199], v[88:91]
	v_mfma_f32_16x16x32_bf16 v[76:79], v[132:135], v[212:215], v[76:79]
	v_mfma_f32_16x16x32_bf16 v[72:75], v[140:143], v[212:215], v[72:75]
	s_setprio 1
	s_setprio 0
	v_mfma_f32_16x16x32_bf16 v[116:119], v[144:147], v[160:163], v[116:119]
	v_mfma_f32_16x16x32_bf16 v[112:115], v[152:155], v[160:163], v[112:115]
	v_mfma_f32_16x16x32_bf16 v[100:103], v[144:147], v[168:171], v[100:103]
	v_mfma_f32_16x16x32_bf16 v[96:99], v[152:155], v[168:171], v[96:99]
	v_mfma_f32_16x16x32_bf16 v[84:87], v[144:147], v[192:195], v[84:87]
	v_mfma_f32_16x16x32_bf16 v[80:83], v[152:155], v[192:195], v[80:83]
	v_mfma_f32_16x16x32_bf16 v[68:71], v[144:147], v[200:203], v[68:71]
	v_mfma_f32_16x16x32_bf16 v[64:67], v[152:155], v[200:203], v[64:67]
	v_mfma_f32_16x16x32_bf16 v[116:119], v[148:151], v[164:167], v[116:119]
	v_mfma_f32_16x16x32_bf16 v[112:115], v[156:159], v[164:167], v[112:115]
	v_mfma_f32_16x16x32_bf16 v[100:103], v[148:151], v[172:175], v[100:103]
	v_mfma_f32_16x16x32_bf16 v[96:99], v[156:159], v[172:175], v[96:99]
	v_mfma_f32_16x16x32_bf16 v[84:87], v[148:151], v[196:199], v[84:87]
	v_mfma_f32_16x16x32_bf16 v[80:83], v[156:159], v[196:199], v[80:83]
	v_mfma_f32_16x16x32_bf16 v[68:71], v[148:151], v[212:215], v[68:71]
	v_mfma_f32_16x16x32_bf16 v[64:67], v[156:159], v[212:215], v[64:67]
	s_setprio 1
	s_barrier
	s_add_i32 s58, s51, s30
	v_lshl_add_u64 v[216:217], s[42:43], 0, v[178:179]
	s_mov_b32 m0, s58
	ds_read_b128 v[160:163], v211 offset:16384
	ds_read_b128 v[164:167], v211 offset:17408
	ds_read_b128 v[168:171], v211 offset:18432
	ds_read_b128 v[172:175], v211 offset:19456
	ds_read_b128 v[192:195], v211 offset:20480
	ds_read_b128 v[196:199], v211 offset:21504
	ds_read_b128 v[200:203], v211 offset:22528
	ds_read_b128 v[212:215], v211 offset:23552
	global_load_lds_dwordx4 v[216:217], off
	s_add_i32 m0, s58, 0x2000
	s_add_u32 s58, s42, 0x40000
	v_lshl_add_u64 v[218:219], s[42:43], 0, v[182:183]
	s_addc_u32 s59, s43, 0
	s_add_i32 s60, s52, s30
	global_load_lds_dwordx4 v[218:219], off
	v_lshl_add_u64 v[220:221], s[58:59], 0, v[178:179]
	s_mov_b32 m0, s60
	v_lshl_add_u64 v[222:223], s[44:45], 0, v[180:181]
	global_load_lds_dwordx4 v[220:221], off
	v_lshl_add_u64 v[220:221], s[58:59], 0, v[182:183]
	s_add_i32 m0, s60, 0x2000
	s_nop 0
	global_load_lds_dwordx4 v[220:221], off
	v_lshl_add_u64 v[220:221], s[44:45], 0, v[176:177]
	s_mov_b32 m0, s31
	s_nop 0
	global_load_lds_dwordx4 v[220:221], off
	s_mov_b32 m0, s33
	s_nop 0
	global_load_lds_dwordx4 v[222:223], off
	s_waitcnt vmcnt(8)
	s_waitcnt lgkmcnt(0)
	s_barrier
	s_setprio 0
	s_waitcnt lgkmcnt(0)
	v_mfma_f32_16x16x32_bf16 v[60:63], v[128:131], v[160:163], v[60:63]
	v_mfma_f32_16x16x32_bf16 v[56:59], v[136:139], v[160:163], v[56:59]
	v_mfma_f32_16x16x32_bf16 v[44:47], v[128:131], v[168:171], v[44:47]
	v_mfma_f32_16x16x32_bf16 v[40:43], v[136:139], v[168:171], v[40:43]
	v_mfma_f32_16x16x32_bf16 v[28:31], v[128:131], v[192:195], v[28:31]
	v_mfma_f32_16x16x32_bf16 v[24:27], v[136:139], v[192:195], v[24:27]
	v_mfma_f32_16x16x32_bf16 v[12:15], v[128:131], v[200:203], v[12:15]
	v_mfma_f32_16x16x32_bf16 v[8:11], v[136:139], v[200:203], v[8:11]
	v_mfma_f32_16x16x32_bf16 v[60:63], v[132:135], v[164:167], v[60:63]
	v_mfma_f32_16x16x32_bf16 v[56:59], v[140:143], v[164:167], v[56:59]
	v_mfma_f32_16x16x32_bf16 v[44:47], v[132:135], v[172:175], v[44:47]
	v_mfma_f32_16x16x32_bf16 v[40:43], v[140:143], v[172:175], v[40:43]
	v_mfma_f32_16x16x32_bf16 v[28:31], v[132:135], v[196:199], v[28:31]
	v_mfma_f32_16x16x32_bf16 v[24:27], v[140:143], v[196:199], v[24:27]
	v_mfma_f32_16x16x32_bf16 v[12:15], v[132:135], v[212:215], v[12:15]
	v_mfma_f32_16x16x32_bf16 v[8:11], v[140:143], v[212:215], v[8:11]
	s_setprio 1
	s_setprio 0
	v_mfma_f32_16x16x32_bf16 v[52:55], v[144:147], v[160:163], v[52:55]
	v_mfma_f32_16x16x32_bf16 v[48:51], v[152:155], v[160:163], v[48:51]
	v_mfma_f32_16x16x32_bf16 v[36:39], v[144:147], v[168:171], v[36:39]
	v_mfma_f32_16x16x32_bf16 v[32:35], v[152:155], v[168:171], v[32:35]
	v_mfma_f32_16x16x32_bf16 v[20:23], v[144:147], v[192:195], v[20:23]
	v_mfma_f32_16x16x32_bf16 v[16:19], v[152:155], v[192:195], v[16:19]
	v_mfma_f32_16x16x32_bf16 v[4:7], v[144:147], v[200:203], v[4:7]
	v_mfma_f32_16x16x32_bf16 v[0:3], v[152:155], v[200:203], v[0:3]
	v_mfma_f32_16x16x32_bf16 v[52:55], v[148:151], v[164:167], v[52:55]
	v_mfma_f32_16x16x32_bf16 v[48:51], v[156:159], v[164:167], v[48:51]
	v_mfma_f32_16x16x32_bf16 v[36:39], v[148:151], v[172:175], v[36:39]
	v_mfma_f32_16x16x32_bf16 v[32:35], v[156:159], v[172:175], v[32:35]
	v_mfma_f32_16x16x32_bf16 v[20:23], v[148:151], v[196:199], v[20:23]
	v_mfma_f32_16x16x32_bf16 v[16:19], v[156:159], v[196:199], v[16:19]
	v_mfma_f32_16x16x32_bf16 v[4:7], v[148:151], v[212:215], v[4:7]
	v_mfma_f32_16x16x32_bf16 v[0:3], v[156:159], v[212:215], v[0:3]
	s_setprio 1
	s_barrier
	s_add_i32 s58, 0, 0x18000
	s_add_i32 s59, 0, 0x1c000
	v_add_u32_e32 v140, s58, v205
	v_add_u32_e32 v156, s59, v205
	ds_read_b128 v[128:131], v140
	ds_read_b128 v[132:135], v140 offset:1024
	ds_read_b128 v[136:139], v140 offset:2048
	ds_read_b128 v[140:143], v140 offset:3072
	ds_read_b128 v[144:147], v156
	ds_read_b128 v[148:151], v156 offset:1024
	ds_read_b128 v[152:155], v156 offset:2048
	ds_read_b128 v[156:159], v156 offset:3072
	s_add_u32 s44, s44, 0x40000
	s_addc_u32 s45, s45, 0
	s_mov_b32 m0, s34
	v_lshl_add_u64 v[224:225], s[44:45], 0, v[176:177]
	ds_read_b128 v[160:163], v211 offset:32768
	ds_read_b128 v[164:167], v211 offset:33792
	ds_read_b128 v[168:171], v211 offset:34816
	ds_read_b128 v[172:175], v211 offset:35840
	ds_read_b128 v[192:195], v211 offset:36864
	ds_read_b128 v[196:199], v211 offset:37888
	ds_read_b128 v[200:203], v211 offset:38912
	ds_read_b128 v[212:215], v211 offset:39936
	global_load_lds_dwordx4 v[224:225], off
	v_lshl_add_u64 v[224:225], s[44:45], 0, v[180:181]
	s_mov_b32 m0, s35
	s_nop 0
	global_load_lds_dwordx4 v[224:225], off
	s_waitcnt vmcnt(8)
	s_waitcnt lgkmcnt(0)
	s_barrier
	s_setprio 0
	s_waitcnt lgkmcnt(0)
	v_mfma_f32_16x16x32_bf16 v[124:127], v[128:131], v[160:163], v[124:127]
	v_mfma_f32_16x16x32_bf16 v[120:123], v[136:139], v[160:163], v[120:123]
	v_mfma_f32_16x16x32_bf16 v[108:111], v[128:131], v[168:171], v[108:111]
	v_mfma_f32_16x16x32_bf16 v[104:107], v[136:139], v[168:171], v[104:107]
	v_mfma_f32_16x16x32_bf16 v[92:95], v[128:131], v[192:195], v[92:95]
	v_mfma_f32_16x16x32_bf16 v[88:91], v[136:139], v[192:195], v[88:91]
	v_mfma_f32_16x16x32_bf16 v[76:79], v[128:131], v[200:203], v[76:79]
	v_mfma_f32_16x16x32_bf16 v[72:75], v[136:139], v[200:203], v[72:75]
	v_mfma_f32_16x16x32_bf16 v[124:127], v[132:135], v[164:167], v[124:127]
	v_mfma_f32_16x16x32_bf16 v[120:123], v[140:143], v[164:167], v[120:123]
	v_mfma_f32_16x16x32_bf16 v[108:111], v[132:135], v[172:175], v[108:111]
	v_mfma_f32_16x16x32_bf16 v[104:107], v[140:143], v[172:175], v[104:107]
	v_mfma_f32_16x16x32_bf16 v[92:95], v[132:135], v[196:199], v[92:95]
	v_mfma_f32_16x16x32_bf16 v[88:91], v[140:143], v[196:199], v[88:91]
	v_mfma_f32_16x16x32_bf16 v[76:79], v[132:135], v[212:215], v[76:79]
	v_mfma_f32_16x16x32_bf16 v[72:75], v[140:143], v[212:215], v[72:75]
	s_setprio 1
	s_setprio 0
	v_mfma_f32_16x16x32_bf16 v[116:119], v[144:147], v[160:163], v[116:119]
	v_mfma_f32_16x16x32_bf16 v[112:115], v[152:155], v[160:163], v[112:115]
	v_mfma_f32_16x16x32_bf16 v[100:103], v[144:147], v[168:171], v[100:103]
	v_mfma_f32_16x16x32_bf16 v[96:99], v[152:155], v[168:171], v[96:99]
	v_mfma_f32_16x16x32_bf16 v[84:87], v[144:147], v[192:195], v[84:87]
	v_mfma_f32_16x16x32_bf16 v[80:83], v[152:155], v[192:195], v[80:83]
	v_mfma_f32_16x16x32_bf16 v[68:71], v[144:147], v[200:203], v[68:71]
	v_mfma_f32_16x16x32_bf16 v[64:67], v[152:155], v[200:203], v[64:67]
	v_mfma_f32_16x16x32_bf16 v[116:119], v[148:151], v[164:167], v[116:119]
	v_mfma_f32_16x16x32_bf16 v[112:115], v[156:159], v[164:167], v[112:115]
	v_mfma_f32_16x16x32_bf16 v[100:103], v[148:151], v[172:175], v[100:103]
	v_mfma_f32_16x16x32_bf16 v[96:99], v[156:159], v[172:175], v[96:99]
	v_mfma_f32_16x16x32_bf16 v[84:87], v[148:151], v[196:199], v[84:87]
	v_mfma_f32_16x16x32_bf16 v[80:83], v[156:159], v[196:199], v[80:83]
	v_mfma_f32_16x16x32_bf16 v[68:71], v[148:151], v[212:215], v[68:71]
	v_mfma_f32_16x16x32_bf16 v[64:67], v[156:159], v[212:215], v[64:67]
	s_setprio 1
	s_barrier
	s_add_i32 s44, s58, s30
	v_lshl_add_u64 v[216:217], v[216:217], 0, s[16:17]
	s_mov_b32 m0, s44
	ds_read_b128 v[160:163], v211 offset:49152
	ds_read_b128 v[164:167], v211 offset:50176
	ds_read_b128 v[168:171], v211 offset:51200
	ds_read_b128 v[172:175], v211 offset:52224
	ds_read_b128 v[192:195], v211 offset:53248
	ds_read_b128 v[196:199], v211 offset:54272
	ds_read_b128 v[200:203], v211 offset:55296
	ds_read_b128 v[212:215], v211 offset:56320
	global_load_lds_dwordx4 v[216:217], off
	s_add_i32 m0, s44, 0x2000
	s_add_u32 s42, s42, 0x40080
	v_lshl_add_u64 v[216:217], v[218:219], 0, s[16:17]
	s_addc_u32 s43, s43, 0
	s_add_i32 s44, s59, s30
	global_load_lds_dwordx4 v[216:217], off
	v_lshl_add_u64 v[216:217], s[42:43], 0, v[178:179]
	s_mov_b32 m0, s44
	s_nop 0
	global_load_lds_dwordx4 v[216:217], off
	v_lshl_add_u64 v[216:217], s[42:43], 0, v[182:183]
	s_add_i32 m0, s44, 0x2000
	s_nop 0
	global_load_lds_dwordx4 v[216:217], off
	v_lshl_add_u64 v[216:217], v[220:221], 0, s[16:17]
	s_mov_b32 m0, s49
	s_nop 0
	global_load_lds_dwordx4 v[216:217], off
	v_lshl_add_u64 v[216:217], v[222:223], 0, s[16:17]
	s_mov_b32 m0, s50
	s_nop 0
	global_load_lds_dwordx4 v[216:217], off
	s_waitcnt vmcnt(8)
	s_waitcnt lgkmcnt(0)
	s_barrier
	s_setprio 0
	s_waitcnt lgkmcnt(0)
	v_mfma_f32_16x16x32_bf16 v[60:63], v[128:131], v[160:163], v[60:63]
	v_mfma_f32_16x16x32_bf16 v[56:59], v[136:139], v[160:163], v[56:59]
	v_mfma_f32_16x16x32_bf16 v[44:47], v[128:131], v[168:171], v[44:47]
	v_mfma_f32_16x16x32_bf16 v[40:43], v[136:139], v[168:171], v[40:43]
	v_mfma_f32_16x16x32_bf16 v[28:31], v[128:131], v[192:195], v[28:31]
	v_mfma_f32_16x16x32_bf16 v[24:27], v[136:139], v[192:195], v[24:27]
	v_mfma_f32_16x16x32_bf16 v[12:15], v[128:131], v[200:203], v[12:15]
	v_mfma_f32_16x16x32_bf16 v[8:11], v[136:139], v[200:203], v[8:11]
	v_mfma_f32_16x16x32_bf16 v[60:63], v[132:135], v[164:167], v[60:63]
	v_mfma_f32_16x16x32_bf16 v[56:59], v[140:143], v[164:167], v[56:59]
	v_mfma_f32_16x16x32_bf16 v[44:47], v[132:135], v[172:175], v[44:47]
	v_mfma_f32_16x16x32_bf16 v[40:43], v[140:143], v[172:175], v[40:43]
	v_mfma_f32_16x16x32_bf16 v[28:31], v[132:135], v[196:199], v[28:31]
	v_mfma_f32_16x16x32_bf16 v[24:27], v[140:143], v[196:199], v[24:27]
	v_mfma_f32_16x16x32_bf16 v[12:15], v[132:135], v[212:215], v[12:15]
	v_mfma_f32_16x16x32_bf16 v[8:11], v[140:143], v[212:215], v[8:11]
	s_setprio 1
	s_setprio 0
	v_mfma_f32_16x16x32_bf16 v[52:55], v[144:147], v[160:163], v[52:55]
	v_mfma_f32_16x16x32_bf16 v[48:51], v[152:155], v[160:163], v[48:51]
	v_mfma_f32_16x16x32_bf16 v[36:39], v[144:147], v[168:171], v[36:39]
	v_mfma_f32_16x16x32_bf16 v[32:35], v[152:155], v[168:171], v[32:35]
	v_mfma_f32_16x16x32_bf16 v[20:23], v[144:147], v[192:195], v[20:23]
	v_mfma_f32_16x16x32_bf16 v[16:19], v[152:155], v[192:195], v[16:19]
	v_mfma_f32_16x16x32_bf16 v[4:7], v[144:147], v[200:203], v[4:7]
	v_mfma_f32_16x16x32_bf16 v[0:3], v[152:155], v[200:203], v[0:3]
	v_mfma_f32_16x16x32_bf16 v[52:55], v[148:151], v[164:167], v[52:55]
	v_mfma_f32_16x16x32_bf16 v[48:51], v[156:159], v[164:167], v[48:51]
	v_mfma_f32_16x16x32_bf16 v[36:39], v[148:151], v[172:175], v[36:39]
	v_mfma_f32_16x16x32_bf16 v[32:35], v[156:159], v[172:175], v[32:35]
	v_mfma_f32_16x16x32_bf16 v[20:23], v[148:151], v[196:199], v[20:23]
	v_mfma_f32_16x16x32_bf16 v[16:19], v[156:159], v[196:199], v[16:19]
	v_mfma_f32_16x16x32_bf16 v[4:7], v[148:151], v[212:215], v[4:7]
	v_mfma_f32_16x16x32_bf16 v[0:3], v[156:159], v[212:215], v[0:3]
	s_setprio 1
	s_barrier
	s_add_i32 s57, s57, 2
	s_add_u32 s40, s40, 0x100
	s_addc_u32 s41, s41, 0
	s_add_u32 s55, s55, 0x100
	s_addc_u32 s56, s56, 0
	s_cmp_gt_u32 s57, 13
	s_cbranch_scc0 .LBB5_536
	s_setprio 0
	s_nop 0
	s_nop 0
	s_nop 0
	s_nop 0
	s_nop 0
	s_nop 0
	s_nop 0
	s_nop 0
	s_nop 0
	s_nop 0
	s_nop 0
	s_nop 0
	s_nop 0
	s_and_b64 vcc, exec, s[14:15]
	s_cbranch_vccz .LBB5_539
	s_barrier

.Lskw_P5:
	s_waitcnt lgkmcnt(0)
	s_barrier
	s_setprio 0
	s_waitcnt lgkmcnt(0)
	v_mfma_f32_16x16x32_bf16 v[140:143], v[32:35], v[192:195], v[140:143]
	v_mfma_f32_16x16x32_bf16 v[136:139], v[40:43], v[192:195], v[136:139]
	v_mfma_f32_16x16x32_bf16 v[124:127], v[32:35], v[200:203], v[124:127]
	v_mfma_f32_16x16x32_bf16 v[120:123], v[40:43], v[200:203], v[120:123]
	v_mfma_f32_16x16x32_bf16 v[108:111], v[32:35], v[208:211], v[108:111]
	v_mfma_f32_16x16x32_bf16 v[104:107], v[40:43], v[208:211], v[104:107]
	v_mfma_f32_16x16x32_bf16 v[92:95], v[32:35], v[216:219], v[92:95]
	v_mfma_f32_16x16x32_bf16 v[88:91], v[40:43], v[216:219], v[88:91]
	v_mfma_f32_16x16x32_bf16 v[140:143], v[36:39], v[196:199], v[140:143]
	v_mfma_f32_16x16x32_bf16 v[136:139], v[44:47], v[196:199], v[136:139]
	v_mfma_f32_16x16x32_bf16 v[124:127], v[36:39], v[204:207], v[124:127]
	v_mfma_f32_16x16x32_bf16 v[120:123], v[44:47], v[204:207], v[120:123]
	v_mfma_f32_16x16x32_bf16 v[108:111], v[36:39], v[212:215], v[108:111]
	v_mfma_f32_16x16x32_bf16 v[104:107], v[44:47], v[212:215], v[104:107]
	v_mfma_f32_16x16x32_bf16 v[92:95], v[36:39], v[220:223], v[92:95]
	v_mfma_f32_16x16x32_bf16 v[88:91], v[44:47], v[220:223], v[88:91]
	s_setprio 1
	s_setprio 0
	v_mfma_f32_16x16x32_bf16 v[132:135], v[144:147], v[192:195], v[132:135]
	v_mfma_f32_16x16x32_bf16 v[128:131], v[152:155], v[192:195], v[128:131]
	v_mfma_f32_16x16x32_bf16 v[116:119], v[144:147], v[200:203], v[116:119]
	v_mfma_f32_16x16x32_bf16 v[112:115], v[152:155], v[200:203], v[112:115]
	v_mfma_f32_16x16x32_bf16 v[100:103], v[144:147], v[208:211], v[100:103]
	v_mfma_f32_16x16x32_bf16 v[96:99], v[152:155], v[208:211], v[96:99]
	v_mfma_f32_16x16x32_bf16 v[84:87], v[144:147], v[216:219], v[84:87]
	v_mfma_f32_16x16x32_bf16 v[80:83], v[152:155], v[216:219], v[80:83]
	v_mfma_f32_16x16x32_bf16 v[132:135], v[148:151], v[196:199], v[132:135]
	v_mfma_f32_16x16x32_bf16 v[128:131], v[156:159], v[196:199], v[128:131]
	v_mfma_f32_16x16x32_bf16 v[116:119], v[148:151], v[204:207], v[116:119]
	v_mfma_f32_16x16x32_bf16 v[112:115], v[156:159], v[204:207], v[112:115]
	v_mfma_f32_16x16x32_bf16 v[100:103], v[148:151], v[212:215], v[100:103]
	v_mfma_f32_16x16x32_bf16 v[96:99], v[156:159], v[212:215], v[96:99]
	v_mfma_f32_16x16x32_bf16 v[84:87], v[148:151], v[220:223], v[84:87]
	v_mfma_f32_16x16x32_bf16 v[80:83], v[156:159], v[220:223], v[80:83]
	s_setprio 1
	s_barrier
	s_add_i32 s34, s80, s60
	v_lshl_add_u64 v[180:181], s[8:9], 0, v[162:163]
	s_mov_b32 m0, s34
	ds_read_b128 v[192:195], v188 offset:16384
	ds_read_b128 v[196:199], v188 offset:17408
	ds_read_b128 v[200:203], v188 offset:18432
	ds_read_b128 v[204:207], v188 offset:19456
	ds_read_b128 v[208:211], v188 offset:20480
	ds_read_b128 v[212:215], v188 offset:21504
	ds_read_b128 v[216:219], v188 offset:22528
	ds_read_b128 v[220:223], v188 offset:23552
	global_load_lds_dwordx4 v[180:181], off
	s_add_i32 m0, s34, 0x2000
	s_add_u32 s34, s8, 0x40000
	v_lshl_add_u64 v[224:225], s[8:9], 0, v[166:167]
	s_addc_u32 s35, s9, 0
	s_add_i32 s49, s81, s60
	global_load_lds_dwordx4 v[224:225], off
	v_lshl_add_u64 v[226:227], s[34:35], 0, v[162:163]
	s_mov_b32 m0, s49
	v_lshl_add_u64 v[228:229], s[56:57], 0, v[164:165]
	global_load_lds_dwordx4 v[226:227], off
	v_lshl_add_u64 v[226:227], s[34:35], 0, v[166:167]
	s_add_i32 m0, s49, 0x2000
	s_nop 0
	global_load_lds_dwordx4 v[226:227], off
	v_lshl_add_u64 v[226:227], s[56:57], 0, v[160:161]
	s_mov_b32 m0, s61
	s_nop 0
	global_load_lds_dwordx4 v[226:227], off
	s_mov_b32 m0, s62
	s_nop 0
	global_load_lds_dwordx4 v[228:229], off
	s_waitcnt vmcnt(8)
	s_waitcnt lgkmcnt(0)
	s_barrier
	s_setprio 0
	s_waitcnt lgkmcnt(0)
	v_mfma_f32_16x16x32_bf16 v[76:79], v[32:35], v[192:195], v[76:79]
	v_mfma_f32_16x16x32_bf16 v[72:75], v[40:43], v[192:195], v[72:75]
	v_mfma_f32_16x16x32_bf16 v[60:63], v[32:35], v[200:203], v[60:63]
	v_mfma_f32_16x16x32_bf16 v[56:59], v[40:43], v[200:203], v[56:59]
	v_mfma_f32_16x16x32_bf16 v[28:31], v[32:35], v[208:211], v[28:31]
	v_mfma_f32_16x16x32_bf16 v[24:27], v[40:43], v[208:211], v[24:27]
	v_mfma_f32_16x16x32_bf16 v[12:15], v[32:35], v[216:219], v[12:15]
	v_mfma_f32_16x16x32_bf16 v[8:11], v[40:43], v[216:219], v[8:11]
	v_mfma_f32_16x16x32_bf16 v[76:79], v[36:39], v[196:199], v[76:79]
	v_mfma_f32_16x16x32_bf16 v[72:75], v[44:47], v[196:199], v[72:75]
	v_mfma_f32_16x16x32_bf16 v[60:63], v[36:39], v[204:207], v[60:63]
	v_mfma_f32_16x16x32_bf16 v[56:59], v[44:47], v[204:207], v[56:59]
	v_mfma_f32_16x16x32_bf16 v[28:31], v[36:39], v[212:215], v[28:31]
	v_mfma_f32_16x16x32_bf16 v[24:27], v[44:47], v[212:215], v[24:27]
	v_mfma_f32_16x16x32_bf16 v[12:15], v[36:39], v[220:223], v[12:15]
	v_mfma_f32_16x16x32_bf16 v[8:11], v[44:47], v[220:223], v[8:11]
	s_setprio 1
	s_setprio 0
	v_mfma_f32_16x16x32_bf16 v[20:23], v[144:147], v[208:211], v[20:23]
	v_mfma_f32_16x16x32_bf16 v[16:19], v[152:155], v[208:211], v[16:19]
	v_mfma_f32_16x16x32_bf16 v[4:7], v[144:147], v[216:219], v[4:7]
	v_mfma_f32_16x16x32_bf16 v[0:3], v[152:155], v[216:219], v[0:3]
	v_mfma_f32_16x16x32_bf16 v[32:35], v[144:147], v[192:195], v[68:71]
	v_mfma_f32_16x16x32_bf16 v[36:39], v[152:155], v[192:195], v[64:67]
	v_mfma_f32_16x16x32_bf16 v[40:43], v[144:147], v[200:203], v[52:55]
	v_mfma_f32_16x16x32_bf16 v[44:47], v[152:155], v[200:203], v[48:51]
	v_mfma_f32_16x16x32_bf16 v[20:23], v[148:151], v[212:215], v[20:23]
	v_mfma_f32_16x16x32_bf16 v[16:19], v[156:159], v[212:215], v[16:19]
	v_mfma_f32_16x16x32_bf16 v[4:7], v[148:151], v[220:223], v[4:7]
	v_mfma_f32_16x16x32_bf16 v[0:3], v[156:159], v[220:223], v[0:3]
	v_mfma_f32_16x16x32_bf16 v[32:35], v[148:151], v[196:199], v[32:35]
	v_mfma_f32_16x16x32_bf16 v[36:39], v[156:159], v[196:199], v[36:39]
	v_mfma_f32_16x16x32_bf16 v[40:43], v[148:151], v[204:207], v[40:43]
	v_mfma_f32_16x16x32_bf16 v[44:47], v[156:159], v[204:207], v[44:47]
	s_setprio 1
	s_barrier
	s_add_i32 s49, 0, 0x18000
	s_add_i32 s51, 0, 0x1c000
	v_add_u32_e32 v68, s49, v183
	v_add_u32_e32 v156, s51, v183
	ds_read_b128 v[48:51], v68
	ds_read_b128 v[52:55], v68 offset:1024
	ds_read_b128 v[64:67], v68 offset:2048
	ds_read_b128 v[68:71], v68 offset:3072
	ds_read_b128 v[144:147], v156
	ds_read_b128 v[148:151], v156 offset:1024
	ds_read_b128 v[152:155], v156 offset:2048
	ds_read_b128 v[156:159], v156 offset:3072
	s_add_u32 s34, s56, 0x40000
	s_addc_u32 s35, s57, 0
	s_mov_b32 m0, s63
	v_lshl_add_u64 v[230:231], s[34:35], 0, v[160:161]
	ds_read_b128 v[192:195], v188 offset:32768
	ds_read_b128 v[196:199], v188 offset:33792
	ds_read_b128 v[200:203], v188 offset:34816
	ds_read_b128 v[204:207], v188 offset:35840
	ds_read_b128 v[208:211], v188 offset:36864
	ds_read_b128 v[212:215], v188 offset:37888
	ds_read_b128 v[216:219], v188 offset:38912
	ds_read_b128 v[220:223], v188 offset:39936
	global_load_lds_dwordx4 v[230:231], off
	v_lshl_add_u64 v[230:231], s[34:35], 0, v[164:165]
	s_mov_b32 m0, s64
	s_nop 0
	global_load_lds_dwordx4 v[230:231], off
	s_waitcnt vmcnt(8)
	s_waitcnt lgkmcnt(0)
	s_barrier
	s_setprio 0
	s_waitcnt lgkmcnt(0)
	v_mfma_f32_16x16x32_bf16 v[140:143], v[48:51], v[192:195], v[140:143]
	v_mfma_f32_16x16x32_bf16 v[136:139], v[64:67], v[192:195], v[136:139]
	v_mfma_f32_16x16x32_bf16 v[124:127], v[48:51], v[200:203], v[124:127]
	v_mfma_f32_16x16x32_bf16 v[120:123], v[64:67], v[200:203], v[120:123]
	v_mfma_f32_16x16x32_bf16 v[108:111], v[48:51], v[208:211], v[108:111]
	v_mfma_f32_16x16x32_bf16 v[104:107], v[64:67], v[208:211], v[104:107]
	v_mfma_f32_16x16x32_bf16 v[92:95], v[48:51], v[216:219], v[92:95]
	v_mfma_f32_16x16x32_bf16 v[88:91], v[64:67], v[216:219], v[88:91]
	v_mfma_f32_16x16x32_bf16 v[140:143], v[52:55], v[196:199], v[140:143]
	v_mfma_f32_16x16x32_bf16 v[136:139], v[68:71], v[196:199], v[136:139]
	v_mfma_f32_16x16x32_bf16 v[124:127], v[52:55], v[204:207], v[124:127]
	v_mfma_f32_16x16x32_bf16 v[120:123], v[68:71], v[204:207], v[120:123]
	v_mfma_f32_16x16x32_bf16 v[108:111], v[52:55], v[212:215], v[108:111]
	v_mfma_f32_16x16x32_bf16 v[104:107], v[68:71], v[212:215], v[104:107]
	v_mfma_f32_16x16x32_bf16 v[92:95], v[52:55], v[220:223], v[92:95]
	v_mfma_f32_16x16x32_bf16 v[88:91], v[68:71], v[220:223], v[88:91]
	s_setprio 1
	s_setprio 0
	v_mfma_f32_16x16x32_bf16 v[132:135], v[144:147], v[192:195], v[132:135]
	v_mfma_f32_16x16x32_bf16 v[128:131], v[152:155], v[192:195], v[128:131]
	v_mfma_f32_16x16x32_bf16 v[116:119], v[144:147], v[200:203], v[116:119]
	v_mfma_f32_16x16x32_bf16 v[112:115], v[152:155], v[200:203], v[112:115]
	v_mfma_f32_16x16x32_bf16 v[100:103], v[144:147], v[208:211], v[100:103]
	v_mfma_f32_16x16x32_bf16 v[96:99], v[152:155], v[208:211], v[96:99]
	v_mfma_f32_16x16x32_bf16 v[84:87], v[144:147], v[216:219], v[84:87]
	v_mfma_f32_16x16x32_bf16 v[80:83], v[152:155], v[216:219], v[80:83]
	v_mfma_f32_16x16x32_bf16 v[132:135], v[148:151], v[196:199], v[132:135]
	v_mfma_f32_16x16x32_bf16 v[128:131], v[156:159], v[196:199], v[128:131]
	v_mfma_f32_16x16x32_bf16 v[116:119], v[148:151], v[204:207], v[116:119]
	v_mfma_f32_16x16x32_bf16 v[112:115], v[156:159], v[204:207], v[112:115]
	v_mfma_f32_16x16x32_bf16 v[100:103], v[148:151], v[212:215], v[100:103]
	v_mfma_f32_16x16x32_bf16 v[96:99], v[156:159], v[212:215], v[96:99]
	v_mfma_f32_16x16x32_bf16 v[84:87], v[148:151], v[220:223], v[84:87]
	v_mfma_f32_16x16x32_bf16 v[80:83], v[156:159], v[220:223], v[80:83]
	s_setprio 1
	s_barrier
	s_add_i32 s34, s49, s60
	v_lshl_add_u64 v[180:181], v[180:181], 0, s[46:47]
	s_mov_b32 m0, s34
	ds_read_b128 v[192:195], v188 offset:49152
	ds_read_b128 v[196:199], v188 offset:50176
	ds_read_b128 v[200:203], v188 offset:51200
	ds_read_b128 v[204:207], v188 offset:52224
	ds_read_b128 v[208:211], v188 offset:53248
	ds_read_b128 v[212:215], v188 offset:54272
	ds_read_b128 v[216:219], v188 offset:55296
	ds_read_b128 v[220:223], v188 offset:56320
	global_load_lds_dwordx4 v[180:181], off
	s_add_i32 m0, s34, 0x2000
	s_add_u32 s8, s8, 0x40080
	v_lshl_add_u64 v[180:181], v[224:225], 0, s[46:47]
	s_addc_u32 s9, s9, 0
	s_add_i32 s34, s51, s60
	global_load_lds_dwordx4 v[180:181], off
	v_lshl_add_u64 v[180:181], s[8:9], 0, v[162:163]
	s_mov_b32 m0, s34
	s_nop 0
	global_load_lds_dwordx4 v[180:181], off
	v_lshl_add_u64 v[180:181], s[8:9], 0, v[166:167]
	s_add_i32 m0, s34, 0x2000
	s_nop 0
	global_load_lds_dwordx4 v[180:181], off
	v_lshl_add_u64 v[180:181], v[226:227], 0, s[46:47]
	s_mov_b32 m0, s78
	s_nop 0
	global_load_lds_dwordx4 v[180:181], off
	v_lshl_add_u64 v[180:181], v[228:229], 0, s[46:47]
	s_mov_b32 m0, s79
	s_nop 0
	global_load_lds_dwordx4 v[180:181], off
	s_waitcnt vmcnt(8)
	s_waitcnt lgkmcnt(0)
	s_barrier
	s_setprio 0
	s_waitcnt lgkmcnt(0)
	v_mfma_f32_16x16x32_bf16 v[76:79], v[48:51], v[192:195], v[76:79]
	v_mfma_f32_16x16x32_bf16 v[72:75], v[64:67], v[192:195], v[72:75]
	v_mfma_f32_16x16x32_bf16 v[60:63], v[48:51], v[200:203], v[60:63]
	v_mfma_f32_16x16x32_bf16 v[56:59], v[64:67], v[200:203], v[56:59]
	v_mfma_f32_16x16x32_bf16 v[28:31], v[48:51], v[208:211], v[28:31]
	v_mfma_f32_16x16x32_bf16 v[24:27], v[64:67], v[208:211], v[24:27]
	v_mfma_f32_16x16x32_bf16 v[12:15], v[48:51], v[216:219], v[12:15]
	v_mfma_f32_16x16x32_bf16 v[8:11], v[64:67], v[216:219], v[8:11]
	v_mfma_f32_16x16x32_bf16 v[76:79], v[52:55], v[196:199], v[76:79]
	v_mfma_f32_16x16x32_bf16 v[72:75], v[68:71], v[196:199], v[72:75]
	v_mfma_f32_16x16x32_bf16 v[60:63], v[52:55], v[204:207], v[60:63]
	v_mfma_f32_16x16x32_bf16 v[56:59], v[68:71], v[204:207], v[56:59]
	v_mfma_f32_16x16x32_bf16 v[28:31], v[52:55], v[212:215], v[28:31]
	v_mfma_f32_16x16x32_bf16 v[24:27], v[68:71], v[212:215], v[24:27]
	v_mfma_f32_16x16x32_bf16 v[12:15], v[52:55], v[220:223], v[12:15]
	v_mfma_f32_16x16x32_bf16 v[8:11], v[68:71], v[220:223], v[8:11]
	s_setprio 1
	s_setprio 0
	v_mfma_f32_16x16x32_bf16 v[32:35], v[144:147], v[192:195], v[32:35]
	v_mfma_f32_16x16x32_bf16 v[68:71], v[148:151], v[196:199], v[32:35]
	v_mfma_f32_16x16x32_bf16 v[32:35], v[152:155], v[192:195], v[36:39]
	v_mfma_f32_16x16x32_bf16 v[64:67], v[156:159], v[196:199], v[32:35]
	v_mfma_f32_16x16x32_bf16 v[32:35], v[144:147], v[200:203], v[40:43]
	v_mfma_f32_16x16x32_bf16 v[52:55], v[148:151], v[204:207], v[32:35]
	v_mfma_f32_16x16x32_bf16 v[32:35], v[152:155], v[200:203], v[44:47]
	v_mfma_f32_16x16x32_bf16 v[20:23], v[144:147], v[208:211], v[20:23]
	v_mfma_f32_16x16x32_bf16 v[16:19], v[152:155], v[208:211], v[16:19]
	v_mfma_f32_16x16x32_bf16 v[4:7], v[144:147], v[216:219], v[4:7]
	v_mfma_f32_16x16x32_bf16 v[0:3], v[152:155], v[216:219], v[0:3]
	v_mfma_f32_16x16x32_bf16 v[48:51], v[156:159], v[204:207], v[32:35]
	v_mfma_f32_16x16x32_bf16 v[20:23], v[148:151], v[212:215], v[20:23]
	v_mfma_f32_16x16x32_bf16 v[16:19], v[156:159], v[212:215], v[16:19]
	v_mfma_f32_16x16x32_bf16 v[4:7], v[148:151], v[220:223], v[4:7]
	v_mfma_f32_16x16x32_bf16 v[0:3], v[156:159], v[220:223], v[0:3]
	s_setprio 1
	s_barrier
	s_add_i32 s33, s33, 2
	s_add_u32 s6, s6, 0x100
	s_addc_u32 s7, s7, 0
	s_add_u32 s25, s25, 0x100
	s_addc_u32 s30, s30, 0
	s_cmp_gt_u32 s33, 13
	s_cbranch_scc0 .LBB5_625
	s_setprio 0
	s_nop 0
	s_nop 0
	s_nop 0
	s_nop 0
	s_nop 0
	s_nop 0
	s_nop 0
	s_nop 0
	s_nop 0
	s_nop 0
	s_nop 0
	s_nop 0
	s_nop 0
	s_and_b64 vcc, exec, s[42:43]
	s_cbranch_vccz .LBB5_628
	s_barrier

.Lskw_P8:
	s_waitcnt lgkmcnt(0)
	s_barrier
	s_setprio 0
	s_waitcnt lgkmcnt(0)
	v_mfma_f32_16x16x32_bf16 v[124:127], v[128:131], v[176:179], v[124:127]
	v_mfma_f32_16x16x32_bf16 v[120:123], v[136:139], v[176:179], v[120:123]
	v_mfma_f32_16x16x32_bf16 v[108:111], v[128:131], v[194:197], v[108:111]
	v_mfma_f32_16x16x32_bf16 v[104:107], v[136:139], v[194:197], v[104:107]
	v_mfma_f32_16x16x32_bf16 v[92:95], v[128:131], v[202:205], v[92:95]
	v_mfma_f32_16x16x32_bf16 v[88:91], v[136:139], v[202:205], v[88:91]
	v_mfma_f32_16x16x32_bf16 v[76:79], v[128:131], v[210:213], v[76:79]
	v_mfma_f32_16x16x32_bf16 v[72:75], v[136:139], v[210:213], v[72:75]
	v_mfma_f32_16x16x32_bf16 v[124:127], v[132:135], v[180:183], v[124:127]
	v_mfma_f32_16x16x32_bf16 v[120:123], v[140:143], v[180:183], v[120:123]
	v_mfma_f32_16x16x32_bf16 v[108:111], v[132:135], v[198:201], v[108:111]
	v_mfma_f32_16x16x32_bf16 v[104:107], v[140:143], v[198:201], v[104:107]
	v_mfma_f32_16x16x32_bf16 v[92:95], v[132:135], v[206:209], v[92:95]
	v_mfma_f32_16x16x32_bf16 v[88:91], v[140:143], v[206:209], v[88:91]
	v_mfma_f32_16x16x32_bf16 v[76:79], v[132:135], v[214:217], v[76:79]
	v_mfma_f32_16x16x32_bf16 v[72:75], v[140:143], v[214:217], v[72:75]
	s_setprio 1
	s_setprio 0
	v_mfma_f32_16x16x32_bf16 v[116:119], v[144:147], v[176:179], v[116:119]
	v_mfma_f32_16x16x32_bf16 v[112:115], v[168:171], v[176:179], v[112:115]
	v_mfma_f32_16x16x32_bf16 v[100:103], v[144:147], v[194:197], v[100:103]
	v_mfma_f32_16x16x32_bf16 v[96:99], v[168:171], v[194:197], v[96:99]
	v_mfma_f32_16x16x32_bf16 v[84:87], v[144:147], v[202:205], v[84:87]
	v_mfma_f32_16x16x32_bf16 v[80:83], v[168:171], v[202:205], v[80:83]
	v_mfma_f32_16x16x32_bf16 v[68:71], v[144:147], v[210:213], v[68:71]
	v_mfma_f32_16x16x32_bf16 v[64:67], v[168:171], v[210:213], v[64:67]
	v_mfma_f32_16x16x32_bf16 v[116:119], v[148:151], v[180:183], v[116:119]
	v_mfma_f32_16x16x32_bf16 v[112:115], v[172:175], v[180:183], v[112:115]
	v_mfma_f32_16x16x32_bf16 v[100:103], v[148:151], v[198:201], v[100:103]
	v_mfma_f32_16x16x32_bf16 v[96:99], v[172:175], v[198:201], v[96:99]
	v_mfma_f32_16x16x32_bf16 v[84:87], v[148:151], v[206:209], v[84:87]
	v_mfma_f32_16x16x32_bf16 v[80:83], v[172:175], v[206:209], v[80:83]
	v_mfma_f32_16x16x32_bf16 v[68:71], v[148:151], v[214:217], v[68:71]
	v_mfma_f32_16x16x32_bf16 v[64:67], v[172:175], v[214:217], v[64:67]
	s_setprio 1
	s_barrier
	s_add_i32 s58, s51, s33
	v_lshl_add_u64 v[184:185], s[40:41], 0, v[154:155]
	s_mov_b32 m0, s58
	ds_read_b128 v[176:179], v193 offset:16384
	ds_read_b128 v[180:183], v193 offset:17408
	ds_read_b128 v[194:197], v193 offset:18432
	ds_read_b128 v[198:201], v193 offset:19456
	ds_read_b128 v[202:205], v193 offset:20480
	ds_read_b128 v[206:209], v193 offset:21504
	ds_read_b128 v[210:213], v193 offset:22528
	ds_read_b128 v[214:217], v193 offset:23552
	global_load_lds_dwordx4 v[184:185], off
	s_add_i32 m0, s58, 0x2000
	s_add_u32 s58, s40, 0x40000
	v_lshl_add_u64 v[218:219], s[40:41], 0, v[158:159]
	s_addc_u32 s59, s41, 0
	s_add_i32 s60, s52, s33
	global_load_lds_dwordx4 v[218:219], off
	v_lshl_add_u64 v[220:221], s[58:59], 0, v[154:155]
	s_mov_b32 m0, s60
	v_lshl_add_u64 v[222:223], s[42:43], 0, v[156:157]
	global_load_lds_dwordx4 v[220:221], off
	v_lshl_add_u64 v[220:221], s[58:59], 0, v[158:159]
	s_add_i32 m0, s60, 0x2000
	s_nop 0
	global_load_lds_dwordx4 v[220:221], off
	v_lshl_add_u64 v[220:221], s[42:43], 0, v[152:153]
	s_mov_b32 m0, s34
	s_nop 0
	global_load_lds_dwordx4 v[220:221], off
	s_mov_b32 m0, s35
	s_nop 0
	global_load_lds_dwordx4 v[222:223], off
	s_waitcnt vmcnt(8)
	s_waitcnt lgkmcnt(0)
	s_barrier
	s_setprio 0
	s_waitcnt lgkmcnt(0)
	v_mfma_f32_16x16x32_bf16 v[60:63], v[128:131], v[176:179], v[60:63]
	v_mfma_f32_16x16x32_bf16 v[56:59], v[136:139], v[176:179], v[56:59]
	v_mfma_f32_16x16x32_bf16 v[44:47], v[128:131], v[194:197], v[44:47]
	v_mfma_f32_16x16x32_bf16 v[40:43], v[136:139], v[194:197], v[40:43]
	v_mfma_f32_16x16x32_bf16 v[28:31], v[128:131], v[202:205], v[28:31]
	v_mfma_f32_16x16x32_bf16 v[24:27], v[136:139], v[202:205], v[24:27]
	v_mfma_f32_16x16x32_bf16 v[12:15], v[128:131], v[210:213], v[12:15]
	v_mfma_f32_16x16x32_bf16 v[8:11], v[136:139], v[210:213], v[8:11]
	v_mfma_f32_16x16x32_bf16 v[60:63], v[132:135], v[180:183], v[60:63]
	v_mfma_f32_16x16x32_bf16 v[56:59], v[140:143], v[180:183], v[56:59]
	v_mfma_f32_16x16x32_bf16 v[44:47], v[132:135], v[198:201], v[44:47]
	v_mfma_f32_16x16x32_bf16 v[40:43], v[140:143], v[198:201], v[40:43]
	v_mfma_f32_16x16x32_bf16 v[28:31], v[132:135], v[206:209], v[28:31]
	v_mfma_f32_16x16x32_bf16 v[24:27], v[140:143], v[206:209], v[24:27]
	v_mfma_f32_16x16x32_bf16 v[12:15], v[132:135], v[214:217], v[12:15]
	v_mfma_f32_16x16x32_bf16 v[8:11], v[140:143], v[214:217], v[8:11]
	s_setprio 1
	s_setprio 0
	v_mfma_f32_16x16x32_bf16 v[52:55], v[144:147], v[176:179], v[52:55]
	v_mfma_f32_16x16x32_bf16 v[48:51], v[168:171], v[176:179], v[48:51]
	v_mfma_f32_16x16x32_bf16 v[36:39], v[144:147], v[194:197], v[36:39]
	v_mfma_f32_16x16x32_bf16 v[32:35], v[168:171], v[194:197], v[32:35]
	v_mfma_f32_16x16x32_bf16 v[20:23], v[144:147], v[202:205], v[20:23]
	v_mfma_f32_16x16x32_bf16 v[16:19], v[168:171], v[202:205], v[16:19]
	v_mfma_f32_16x16x32_bf16 v[4:7], v[144:147], v[210:213], v[4:7]
	v_mfma_f32_16x16x32_bf16 v[0:3], v[168:171], v[210:213], v[0:3]
	v_mfma_f32_16x16x32_bf16 v[52:55], v[148:151], v[180:183], v[52:55]
	v_mfma_f32_16x16x32_bf16 v[48:51], v[172:175], v[180:183], v[48:51]
	v_mfma_f32_16x16x32_bf16 v[36:39], v[148:151], v[198:201], v[36:39]
	v_mfma_f32_16x16x32_bf16 v[32:35], v[172:175], v[198:201], v[32:35]
	v_mfma_f32_16x16x32_bf16 v[20:23], v[148:151], v[206:209], v[20:23]
	v_mfma_f32_16x16x32_bf16 v[16:19], v[172:175], v[206:209], v[16:19]
	v_mfma_f32_16x16x32_bf16 v[4:7], v[148:151], v[214:217], v[4:7]
	v_mfma_f32_16x16x32_bf16 v[0:3], v[172:175], v[214:217], v[0:3]
	s_setprio 1
	s_barrier
	s_add_i32 s58, 0, 0x18000
	s_add_i32 s59, 0, 0x1c000
	v_add_u32_e32 v140, s58, v187
	v_add_u32_e32 v172, s59, v187
	ds_read_b128 v[128:131], v140
	ds_read_b128 v[132:135], v140 offset:1024
	ds_read_b128 v[136:139], v140 offset:2048
	ds_read_b128 v[140:143], v140 offset:3072
	ds_read_b128 v[144:147], v172
	ds_read_b128 v[148:151], v172 offset:1024
	ds_read_b128 v[168:171], v172 offset:2048
	ds_read_b128 v[172:175], v172 offset:3072
	s_add_u32 s42, s42, 0x40000
	s_addc_u32 s43, s43, 0
	s_mov_b32 m0, s44
	v_lshl_add_u64 v[224:225], s[42:43], 0, v[152:153]
	ds_read_b128 v[176:179], v193 offset:32768
	ds_read_b128 v[180:183], v193 offset:33792
	ds_read_b128 v[194:197], v193 offset:34816
	ds_read_b128 v[198:201], v193 offset:35840
	ds_read_b128 v[202:205], v193 offset:36864
	ds_read_b128 v[206:209], v193 offset:37888
	ds_read_b128 v[210:213], v193 offset:38912
	ds_read_b128 v[214:217], v193 offset:39936
	global_load_lds_dwordx4 v[224:225], off
	v_lshl_add_u64 v[224:225], s[42:43], 0, v[156:157]
	s_mov_b32 m0, s45
	s_nop 0
	global_load_lds_dwordx4 v[224:225], off
	s_waitcnt vmcnt(8)
	s_waitcnt lgkmcnt(0)
	s_barrier
	s_setprio 0
	s_waitcnt lgkmcnt(0)
	v_mfma_f32_16x16x32_bf16 v[124:127], v[128:131], v[176:179], v[124:127]
	v_mfma_f32_16x16x32_bf16 v[120:123], v[136:139], v[176:179], v[120:123]
	v_mfma_f32_16x16x32_bf16 v[108:111], v[128:131], v[194:197], v[108:111]
	v_mfma_f32_16x16x32_bf16 v[104:107], v[136:139], v[194:197], v[104:107]
	v_mfma_f32_16x16x32_bf16 v[92:95], v[128:131], v[202:205], v[92:95]
	v_mfma_f32_16x16x32_bf16 v[88:91], v[136:139], v[202:205], v[88:91]
	v_mfma_f32_16x16x32_bf16 v[76:79], v[128:131], v[210:213], v[76:79]
	v_mfma_f32_16x16x32_bf16 v[72:75], v[136:139], v[210:213], v[72:75]
	v_mfma_f32_16x16x32_bf16 v[124:127], v[132:135], v[180:183], v[124:127]
	v_mfma_f32_16x16x32_bf16 v[120:123], v[140:143], v[180:183], v[120:123]
	v_mfma_f32_16x16x32_bf16 v[108:111], v[132:135], v[198:201], v[108:111]
	v_mfma_f32_16x16x32_bf16 v[104:107], v[140:143], v[198:201], v[104:107]
	v_mfma_f32_16x16x32_bf16 v[92:95], v[132:135], v[206:209], v[92:95]
	v_mfma_f32_16x16x32_bf16 v[88:91], v[140:143], v[206:209], v[88:91]
	v_mfma_f32_16x16x32_bf16 v[76:79], v[132:135], v[214:217], v[76:79]
	v_mfma_f32_16x16x32_bf16 v[72:75], v[140:143], v[214:217], v[72:75]
	s_setprio 1
	s_setprio 0
	v_mfma_f32_16x16x32_bf16 v[116:119], v[144:147], v[176:179], v[116:119]
	v_mfma_f32_16x16x32_bf16 v[112:115], v[168:171], v[176:179], v[112:115]
	v_mfma_f32_16x16x32_bf16 v[100:103], v[144:147], v[194:197], v[100:103]
	v_mfma_f32_16x16x32_bf16 v[96:99], v[168:171], v[194:197], v[96:99]
	v_mfma_f32_16x16x32_bf16 v[84:87], v[144:147], v[202:205], v[84:87]
	v_mfma_f32_16x16x32_bf16 v[80:83], v[168:171], v[202:205], v[80:83]
	v_mfma_f32_16x16x32_bf16 v[68:71], v[144:147], v[210:213], v[68:71]
	v_mfma_f32_16x16x32_bf16 v[64:67], v[168:171], v[210:213], v[64:67]
	v_mfma_f32_16x16x32_bf16 v[116:119], v[148:151], v[180:183], v[116:119]
	v_mfma_f32_16x16x32_bf16 v[112:115], v[172:175], v[180:183], v[112:115]
	v_mfma_f32_16x16x32_bf16 v[100:103], v[148:151], v[198:201], v[100:103]
	v_mfma_f32_16x16x32_bf16 v[96:99], v[172:175], v[198:201], v[96:99]
	v_mfma_f32_16x16x32_bf16 v[84:87], v[148:151], v[206:209], v[84:87]
	v_mfma_f32_16x16x32_bf16 v[80:83], v[172:175], v[206:209], v[80:83]
	v_mfma_f32_16x16x32_bf16 v[68:71], v[148:151], v[214:217], v[68:71]
	v_mfma_f32_16x16x32_bf16 v[64:67], v[172:175], v[214:217], v[64:67]
	s_setprio 1
	s_barrier
	s_add_i32 s42, s58, s33
	v_lshl_add_u64 v[184:185], v[184:185], 0, s[18:19]
	s_mov_b32 m0, s42
	ds_read_b128 v[176:179], v193 offset:49152
	ds_read_b128 v[180:183], v193 offset:50176
	ds_read_b128 v[194:197], v193 offset:51200
	ds_read_b128 v[198:201], v193 offset:52224
	ds_read_b128 v[202:205], v193 offset:53248
	ds_read_b128 v[206:209], v193 offset:54272
	ds_read_b128 v[210:213], v193 offset:55296
	ds_read_b128 v[214:217], v193 offset:56320
	global_load_lds_dwordx4 v[184:185], off
	s_add_i32 m0, s42, 0x2000
	s_add_u32 s40, s40, 0x40080
	v_lshl_add_u64 v[184:185], v[218:219], 0, s[18:19]
	s_addc_u32 s41, s41, 0
	s_add_i32 s42, s59, s33
	global_load_lds_dwordx4 v[184:185], off
	v_lshl_add_u64 v[184:185], s[40:41], 0, v[154:155]
	s_mov_b32 m0, s42
	s_nop 0
	global_load_lds_dwordx4 v[184:185], off
	v_lshl_add_u64 v[184:185], s[40:41], 0, v[158:159]
	s_add_i32 m0, s42, 0x2000
	s_nop 0
	global_load_lds_dwordx4 v[184:185], off
	v_lshl_add_u64 v[184:185], v[220:221], 0, s[18:19]
	s_mov_b32 m0, s49
	s_nop 0
	global_load_lds_dwordx4 v[184:185], off
	v_lshl_add_u64 v[184:185], v[222:223], 0, s[18:19]
	s_mov_b32 m0, s50
	s_nop 0
	global_load_lds_dwordx4 v[184:185], off
	s_waitcnt vmcnt(8)
	s_waitcnt lgkmcnt(0)
	s_barrier
	s_setprio 0
	s_waitcnt lgkmcnt(0)
	v_mfma_f32_16x16x32_bf16 v[60:63], v[128:131], v[176:179], v[60:63]
	v_mfma_f32_16x16x32_bf16 v[56:59], v[136:139], v[176:179], v[56:59]
	v_mfma_f32_16x16x32_bf16 v[44:47], v[128:131], v[194:197], v[44:47]
	v_mfma_f32_16x16x32_bf16 v[40:43], v[136:139], v[194:197], v[40:43]
	v_mfma_f32_16x16x32_bf16 v[28:31], v[128:131], v[202:205], v[28:31]
	v_mfma_f32_16x16x32_bf16 v[24:27], v[136:139], v[202:205], v[24:27]
	v_mfma_f32_16x16x32_bf16 v[12:15], v[128:131], v[210:213], v[12:15]
	v_mfma_f32_16x16x32_bf16 v[8:11], v[136:139], v[210:213], v[8:11]
	v_mfma_f32_16x16x32_bf16 v[60:63], v[132:135], v[180:183], v[60:63]
	v_mfma_f32_16x16x32_bf16 v[56:59], v[140:143], v[180:183], v[56:59]
	v_mfma_f32_16x16x32_bf16 v[44:47], v[132:135], v[198:201], v[44:47]
	v_mfma_f32_16x16x32_bf16 v[40:43], v[140:143], v[198:201], v[40:43]
	v_mfma_f32_16x16x32_bf16 v[28:31], v[132:135], v[206:209], v[28:31]
	v_mfma_f32_16x16x32_bf16 v[24:27], v[140:143], v[206:209], v[24:27]
	v_mfma_f32_16x16x32_bf16 v[12:15], v[132:135], v[214:217], v[12:15]
	v_mfma_f32_16x16x32_bf16 v[8:11], v[140:143], v[214:217], v[8:11]
	s_setprio 1
	s_setprio 0
	v_mfma_f32_16x16x32_bf16 v[52:55], v[144:147], v[176:179], v[52:55]
	v_mfma_f32_16x16x32_bf16 v[48:51], v[168:171], v[176:179], v[48:51]
	v_mfma_f32_16x16x32_bf16 v[36:39], v[144:147], v[194:197], v[36:39]
	v_mfma_f32_16x16x32_bf16 v[32:35], v[168:171], v[194:197], v[32:35]
	v_mfma_f32_16x16x32_bf16 v[20:23], v[144:147], v[202:205], v[20:23]
	v_mfma_f32_16x16x32_bf16 v[16:19], v[168:171], v[202:205], v[16:19]
	v_mfma_f32_16x16x32_bf16 v[4:7], v[144:147], v[210:213], v[4:7]
	v_mfma_f32_16x16x32_bf16 v[0:3], v[168:171], v[210:213], v[0:3]
	v_mfma_f32_16x16x32_bf16 v[52:55], v[148:151], v[180:183], v[52:55]
	v_mfma_f32_16x16x32_bf16 v[48:51], v[172:175], v[180:183], v[48:51]
	v_mfma_f32_16x16x32_bf16 v[36:39], v[148:151], v[198:201], v[36:39]
	v_mfma_f32_16x16x32_bf16 v[32:35], v[172:175], v[198:201], v[32:35]
	v_mfma_f32_16x16x32_bf16 v[20:23], v[148:151], v[206:209], v[20:23]
	v_mfma_f32_16x16x32_bf16 v[16:19], v[172:175], v[206:209], v[16:19]
	v_mfma_f32_16x16x32_bf16 v[4:7], v[148:151], v[214:217], v[4:7]
	v_mfma_f32_16x16x32_bf16 v[0:3], v[172:175], v[214:217], v[0:3]
	s_setprio 1
	s_barrier
	s_add_i32 s57, s57, 2
	s_add_u32 s38, s38, 0x100
	s_addc_u32 s39, s39, 0
	s_add_u32 s55, s55, 0x100
	s_addc_u32 s56, s56, 0
	s_cmp_gt_u32 s57, 13
	s_cbranch_scc0 .LBB5_969
	s_setprio 0
	s_nop 0
	s_nop 0
	s_nop 0
	s_nop 0
	s_nop 0
	s_nop 0
	s_nop 0
	s_nop 0
	s_nop 0
	s_nop 0
	s_nop 0
	s_nop 0
	s_nop 0
	s_and_b64 vcc, exec, s[16:17]
	s_cbranch_vccz .LBB5_972
	s_barrier
